# up-projection operands (H of norm0/norm2, W13A/W13B) stored chunk-major in the workspace: each LDS-DMA wave instruction reads 1 KB of whole cache lines
# speedup vs baseline: 1.1035x; 1.0185x over previous
.LBB0_42:
	s_add_i32 s0, s50, -1
	s_mul_hi_i32 s1, s0, 0x2e8ba2e9
	s_lshr_b32 s2, s1, 31
	s_ashr_i32 s1, s1, 1
	s_add_i32 s4, s1, s2
	s_mov_b32 s2, s4
	v_writelane_b32 v214, s2, 57
	s_mul_i32 s1, s4, 11
	s_sub_i32 s21, s0, s1
	v_writelane_b32 v214, s3, 58
	s_mov_b64 s[2:3], 0
	s_mov_b64 s[0:1], -1
	s_cmp_lt_i32 s21, 5
	v_writelane_b32 v214, s2, 59
	s_nop 1
	v_writelane_b32 v214, s3, 60
	s_cbranch_scc1 .LBB0_167
	s_cmp_gt_i32 s21, 6
	s_cbranch_scc0 .LBB0_57
	v_readlane_b32 s8, v217, 20
	s_cmp_gt_i32 s21, 7
	v_readlane_b32 s9, v217, 21
	s_cbranch_scc0 .LBB0_58
	s_cmp_gt_i32 s21, 8
	s_cbranch_scc0 .LBB0_59
	s_cmp_eq_u32 s21, 9
	s_cbranch_scc0 .LBB0_71
	v_readlane_b32 s11, v217, 0
	v_readlane_b32 s12, v214, 57
	s_and_b32 s14, s11, 7
	s_lshr_b32 s15, s11, 3
	s_mul_hi_u32 s16, s12, 0x3500000
	s_mul_i32 s12, s12, 0x3500000
	s_add_u32 s40, s48, s12
	s_addc_u32 s41, s49, s16
	s_add_u32 s40, s40, 0x11a4e000
	s_addc_u32 s41, s41, 0
	v_and_b32_e32 v141, 15, v142
	v_lshrrev_b32_e32 v139, 4, v142
	v_and_b32_e32 v139, 3, v139
	v_lshlrev_b32_e32 v140, 6, v141
	v_lshl_add_u32 v140, v139, 4, v140
	v_lshrrev_b32_e32 v139, 3, v141
	v_lshlrev_b32_e32 v139, 5, v139
	v_xor_b32_e32 v135, v140, v139
	v_lshrrev_b32_e32 v139, 7, v142
	v_lshl_add_u32 v134, v139, 12, v135
	v_lshrrev_b32_e32 v139, 6, v142
	v_and_b32_e32 v139, 1, v139
	v_lshl_add_u32 v135, v139, 12, v135
	v_add_u32_e32 v135, 0x4000, v135
	v_and_b32_e32 v141, 63, v142
	v_lshrrev_b32_e32 v139, 2, v141
	v_lshrrev_b32_e32 v140, 6, v142
	v_lshlrev_b32_e32 v139, 6, v139
	v_lshl_add_u32 v139, v140, 15, v139
	v_and_b32_e32 v140, 3, v141
	v_lshlrev_b32_e32 v140, 4, v140
	v_lshrrev_b32_e32 v141, 5, v141
	v_lshlrev_b32_e32 v141, 5, v141
	v_xor_b32_e32 v140, v140, v141
	v_add_u32_e32 v136, v139, v140
	v_add_u32_e32 v137, 0x40000, v136
	v_lshrrev_b32_e32 v139, 7, v142
	v_and_b32_e32 v141, 15, v142
	v_lshl_add_u32 v139, v139, 6, v141
	v_mul_u32_u24_e32 v139, 0x1600, v139
	v_lshrrev_b32_e32 v140, 6, v142
	v_and_b32_e32 v140, 1, v140
	v_lshlrev_b32_e32 v140, 6, v140
	v_lshrrev_b32_e32 v141, 4, v142
	v_and_b32_e32 v141, 3, v141
	v_lshl_add_u32 v140, v141, 3, v140
	v_add_u32_e32 v138, v139, v140
	v_and_b32_e32 v141, 1, v141
	v_mul_u32_u24_e32 v141, 24, v141
	v_add_u32_e32 v138, v138, v141
	v_lshlrev_b32_e32 v161, 11, v142
	v_lshrrev_b32_e32 v141, 6, v142
	v_lshlrev_b32_e32 v141, 10, v141
	s_nop 0
	v_readfirstlane_b32 s6, v141
	s_mov_b32 s10, s15
.Lg2_a_item1:
	s_mul_i32 s11, s10, 0x2aab
	s_lshr_b32 s11, s11, 16
	s_mul_i32 s12, s11, 6
	s_sub_u32 s12, s10, s12
	s_mov_b32 s16, 0
	s_and_b32 s17, s14, 3
	s_mul_i32 s17, s17, 6
	s_add_u32 s12, s12, s17
	s_lshl_b32 s12, s12, 8
	s_add_u32 s12, s12, s16
	s_lshr_b32 s17, s14, 2
	s_mul_i32 s17, s17, 22
	s_lshl_b32 s11, s11, 1
	s_add_u32 s11, s11, s17
	s_lshl_b32 s16, s12, 11
	s_add_u32 s0, s24, s16
	s_addc_u32 s1, s25, 0
	s_lshl_b32 s16, s11, 18
	s_add_u32 s2, s40, s16
	s_addc_u32 s3, s41, 0
	s_mul_i32 s16, s12, 0x1600
	s_lshl_b32 s17, s11, 7
	s_add_u32 s16, s16, s17
	s_add_u32 s4, s26, s16
	s_addc_u32 s5, s27, 0
	s_add_u32 m0, s6, 0x0
	s_nop 0
	global_load_lds_dwordx4 v136, s[0:1]
	s_add_u32 m0, s6, 0x2000
	s_nop 0
	global_load_lds_dwordx4 v137, s[0:1]
	s_add_u32 m0, s6, 0x4000
	s_nop 0
	global_load_lds_dwordx4 v136, s[2:3]
	s_add_u32 m0, s6, 0x6000
	s_nop 0
	global_load_lds_dwordx4 v137, s[2:3]
	s_add_u32 s0, s0, 1024
	s_addc_u32 s1, s1, 0
	s_add_u32 s2, s2, 1024
	s_addc_u32 s3, s3, 0
	s_add_u32 m0, s6, 0x8000
	s_nop 0
	global_load_lds_dwordx4 v136, s[0:1]
	s_add_u32 m0, s6, 0xa000
	s_nop 0
	global_load_lds_dwordx4 v137, s[0:1]
	s_add_u32 m0, s6, 0xc000
	s_nop 0
	global_load_lds_dwordx4 v136, s[2:3]
	s_add_u32 m0, s6, 0xe000
	s_nop 0
	global_load_lds_dwordx4 v137, s[2:3]
	s_add_u32 s0, s0, 1024
	s_addc_u32 s1, s1, 0
	s_add_u32 s2, s2, 1024
	s_addc_u32 s3, s3, 0
	s_add_u32 m0, s6, 0x10000
	s_nop 0
	global_load_lds_dwordx4 v136, s[0:1]
	s_add_u32 m0, s6, 0x12000
	s_nop 0
	global_load_lds_dwordx4 v137, s[0:1]
	s_add_u32 m0, s6, 0x14000
	s_nop 0
	global_load_lds_dwordx4 v136, s[2:3]
	s_add_u32 m0, s6, 0x16000
	s_nop 0
	global_load_lds_dwordx4 v137, s[2:3]
	s_add_u32 s0, s0, 1024
	s_addc_u32 s1, s1, 0
	s_add_u32 s2, s2, 1024
	s_addc_u32 s3, s3, 0
	v_mov_b32_e32 v2, 0
	v_mov_b32_e32 v3, 0
	v_mov_b32_e32 v4, 0
	v_mov_b32_e32 v5, 0
	v_mov_b32_e32 v6, 0
	v_mov_b32_e32 v7, 0
	v_mov_b32_e32 v8, 0
	v_mov_b32_e32 v9, 0
	v_mov_b32_e32 v10, 0
	v_mov_b32_e32 v11, 0
	v_mov_b32_e32 v12, 0
	v_mov_b32_e32 v13, 0
	v_mov_b32_e32 v14, 0
	v_mov_b32_e32 v15, 0
	v_mov_b32_e32 v16, 0
	v_mov_b32_e32 v17, 0
	v_mov_b32_e32 v18, 0
	v_mov_b32_e32 v19, 0
	v_mov_b32_e32 v20, 0
	v_mov_b32_e32 v21, 0
	v_mov_b32_e32 v22, 0
	v_mov_b32_e32 v23, 0
	v_mov_b32_e32 v24, 0
	v_mov_b32_e32 v25, 0
	v_mov_b32_e32 v26, 0
	v_mov_b32_e32 v27, 0
	v_mov_b32_e32 v28, 0
	v_mov_b32_e32 v29, 0
	v_mov_b32_e32 v30, 0
	v_mov_b32_e32 v31, 0
	v_mov_b32_e32 v32, 0
	v_mov_b32_e32 v33, 0
	v_mov_b32_e32 v34, 0
	v_mov_b32_e32 v35, 0
	v_mov_b32_e32 v36, 0
	v_mov_b32_e32 v37, 0
	v_mov_b32_e32 v38, 0
	v_mov_b32_e32 v39, 0
	v_mov_b32_e32 v40, 0
	v_mov_b32_e32 v41, 0
	v_mov_b32_e32 v42, 0
	v_mov_b32_e32 v43, 0
	v_mov_b32_e32 v44, 0
	v_mov_b32_e32 v45, 0
	v_mov_b32_e32 v46, 0
	v_mov_b32_e32 v47, 0
	v_mov_b32_e32 v48, 0
	v_mov_b32_e32 v49, 0
	v_mov_b32_e32 v50, 0
	v_mov_b32_e32 v51, 0
	v_mov_b32_e32 v52, 0
	v_mov_b32_e32 v53, 0
	v_mov_b32_e32 v54, 0
	v_mov_b32_e32 v55, 0
	v_mov_b32_e32 v56, 0
	v_mov_b32_e32 v57, 0
	v_mov_b32_e32 v58, 0
	v_mov_b32_e32 v59, 0
	v_mov_b32_e32 v60, 0
	v_mov_b32_e32 v61, 0
	v_mov_b32_e32 v62, 0
	v_mov_b32_e32 v63, 0
	v_mov_b32_e32 v64, 0
	v_mov_b32_e32 v65, 0
	v_mov_b32_e32 v66, 0
	v_mov_b32_e32 v67, 0
	v_mov_b32_e32 v68, 0
	v_mov_b32_e32 v69, 0
	v_mov_b32_e32 v70, 0
	v_mov_b32_e32 v71, 0
	v_mov_b32_e32 v72, 0
	v_mov_b32_e32 v73, 0
	v_mov_b32_e32 v74, 0
	v_mov_b32_e32 v75, 0
	v_mov_b32_e32 v76, 0
	v_mov_b32_e32 v77, 0
	v_mov_b32_e32 v78, 0
	v_mov_b32_e32 v79, 0
	v_mov_b32_e32 v80, 0
	v_mov_b32_e32 v81, 0
	v_mov_b32_e32 v82, 0
	v_mov_b32_e32 v83, 0
	v_mov_b32_e32 v84, 0
	v_mov_b32_e32 v85, 0
	v_mov_b32_e32 v86, 0
	v_mov_b32_e32 v87, 0
	v_mov_b32_e32 v88, 0
	v_mov_b32_e32 v89, 0
	v_mov_b32_e32 v90, 0
	v_mov_b32_e32 v91, 0
	v_mov_b32_e32 v92, 0
	v_mov_b32_e32 v93, 0
	v_mov_b32_e32 v94, 0
	v_mov_b32_e32 v95, 0
	v_mov_b32_e32 v96, 0
	v_mov_b32_e32 v97, 0
	v_mov_b32_e32 v98, 0
	v_mov_b32_e32 v99, 0
	v_mov_b32_e32 v100, 0
	v_mov_b32_e32 v101, 0
	v_mov_b32_e32 v102, 0
	v_mov_b32_e32 v103, 0
	v_mov_b32_e32 v104, 0
	v_mov_b32_e32 v105, 0
	v_mov_b32_e32 v106, 0
	v_mov_b32_e32 v107, 0
	v_mov_b32_e32 v108, 0
	v_mov_b32_e32 v109, 0
	v_mov_b32_e32 v110, 0
	v_mov_b32_e32 v111, 0
	v_mov_b32_e32 v112, 0
	v_mov_b32_e32 v113, 0
	v_mov_b32_e32 v114, 0
	v_mov_b32_e32 v115, 0
	v_mov_b32_e32 v116, 0
	v_mov_b32_e32 v117, 0
	v_mov_b32_e32 v118, 0
	v_mov_b32_e32 v119, 0
	v_mov_b32_e32 v120, 0
	v_mov_b32_e32 v121, 0
	v_mov_b32_e32 v122, 0
	v_mov_b32_e32 v123, 0
	v_mov_b32_e32 v124, 0
	v_mov_b32_e32 v125, 0
	v_mov_b32_e32 v126, 0
	v_mov_b32_e32 v127, 0
	v_mov_b32_e32 v128, 0
	v_mov_b32_e32 v129, 0

.Lg2_a_klB4:
	s_waitcnt vmcnt(8)
	s_barrier
	v_add_u32_e32 v139, 0x0, v134
	v_add_u32_e32 v140, 0x0, v135
	ds_read_b128 v[162:165], v139 offset:0
	ds_read_b128 v[166:169], v139 offset:1024
	ds_read_b128 v[170:173], v139 offset:2048
	ds_read_b128 v[174:177], v139 offset:3072
	ds_read_b128 v[194:197], v140 offset:0
	ds_read_b128 v[198:201], v140 offset:1024
	ds_read_b128 v[202:205], v140 offset:2048
	ds_read_b128 v[206:209], v140 offset:3072
	v_mfma_f32_16x16x32_bf16 v[66:69], v[218:221], v[178:181], v[66:69]
	v_mfma_f32_16x16x32_bf16 v[70:73], v[222:225], v[178:181], v[70:73]
	v_mfma_f32_16x16x32_bf16 v[74:77], v[226:229], v[178:181], v[74:77]
	s_add_u32 m0, s6, 0x18000
	s_nop 0
	global_load_lds_dwordx4 v136, s[0:1]
	v_mfma_f32_16x16x32_bf16 v[78:81], v[230:233], v[178:181], v[78:81]
	v_mfma_f32_16x16x32_bf16 v[82:85], v[218:221], v[182:185], v[82:85]
	v_mfma_f32_16x16x32_bf16 v[86:89], v[222:225], v[182:185], v[86:89]
	v_mfma_f32_16x16x32_bf16 v[90:93], v[226:229], v[182:185], v[90:93]
	s_add_u32 m0, s6, 0x1a000
	s_nop 0
	global_load_lds_dwordx4 v137, s[0:1]
	v_mfma_f32_16x16x32_bf16 v[94:97], v[230:233], v[182:185], v[94:97]
	v_mfma_f32_16x16x32_bf16 v[98:101], v[218:221], v[186:189], v[98:101]
	v_mfma_f32_16x16x32_bf16 v[102:105], v[222:225], v[186:189], v[102:105]
	v_mfma_f32_16x16x32_bf16 v[106:109], v[226:229], v[186:189], v[106:109]
	s_add_u32 m0, s6, 0x1c000
	s_nop 0
	global_load_lds_dwordx4 v136, s[2:3]
	v_mfma_f32_16x16x32_bf16 v[110:113], v[230:233], v[186:189], v[110:113]
	v_mfma_f32_16x16x32_bf16 v[114:117], v[218:221], v[190:193], v[114:117]
	v_mfma_f32_16x16x32_bf16 v[118:121], v[222:225], v[190:193], v[118:121]
	v_mfma_f32_16x16x32_bf16 v[122:125], v[226:229], v[190:193], v[122:125]
	s_add_u32 m0, s6, 0x1e000
	s_nop 0
	global_load_lds_dwordx4 v137, s[2:3]
	v_mfma_f32_16x16x32_bf16 v[126:129], v[230:233], v[190:193], v[126:129]
	s_add_u32 s0, s0, 1024
	s_addc_u32 s1, s1, 0
	s_add_u32 s2, s2, 1024
	s_addc_u32 s3, s3, 0
	ds_read_b128 v[218:221], v140 offset:8192
	ds_read_b128 v[222:225], v140 offset:9216
	ds_read_b128 v[226:229], v140 offset:10240
	ds_read_b128 v[230:233], v140 offset:11264
	s_waitcnt lgkmcnt(4)
	v_mfma_f32_16x16x32_bf16 v[2:5], v[194:197], v[162:165], v[2:5]
	v_mfma_f32_16x16x32_bf16 v[6:9], v[198:201], v[162:165], v[6:9]
	v_mfma_f32_16x16x32_bf16 v[10:13], v[202:205], v[162:165], v[10:13]
	v_mfma_f32_16x16x32_bf16 v[14:17], v[206:209], v[162:165], v[14:17]
	v_mfma_f32_16x16x32_bf16 v[18:21], v[194:197], v[166:169], v[18:21]
	v_mfma_f32_16x16x32_bf16 v[22:25], v[198:201], v[166:169], v[22:25]
	v_mfma_f32_16x16x32_bf16 v[26:29], v[202:205], v[166:169], v[26:29]
	v_mfma_f32_16x16x32_bf16 v[30:33], v[206:209], v[166:169], v[30:33]
	v_mfma_f32_16x16x32_bf16 v[34:37], v[194:197], v[170:173], v[34:37]
	v_mfma_f32_16x16x32_bf16 v[38:41], v[198:201], v[170:173], v[38:41]
	v_mfma_f32_16x16x32_bf16 v[42:45], v[202:205], v[170:173], v[42:45]
	v_mfma_f32_16x16x32_bf16 v[46:49], v[206:209], v[170:173], v[46:49]
	v_mfma_f32_16x16x32_bf16 v[50:53], v[194:197], v[174:177], v[50:53]
	v_mfma_f32_16x16x32_bf16 v[54:57], v[198:201], v[174:177], v[54:57]
	v_mfma_f32_16x16x32_bf16 v[58:61], v[202:205], v[174:177], v[58:61]
	v_mfma_f32_16x16x32_bf16 v[62:65], v[206:209], v[174:177], v[62:65]
	s_waitcnt lgkmcnt(0)
	s_waitcnt vmcnt(8)
	s_barrier
	v_add_u32_e32 v139, 0x8000, v134
	v_add_u32_e32 v140, 0x8000, v135
	ds_read_b128 v[178:181], v139 offset:0
	ds_read_b128 v[182:185], v139 offset:1024
	ds_read_b128 v[186:189], v139 offset:2048
	ds_read_b128 v[190:193], v139 offset:3072
	ds_read_b128 v[194:197], v140 offset:0
	ds_read_b128 v[198:201], v140 offset:1024
	ds_read_b128 v[202:205], v140 offset:2048
	ds_read_b128 v[206:209], v140 offset:3072
	v_mfma_f32_16x16x32_bf16 v[66:69], v[218:221], v[162:165], v[66:69]
	v_mfma_f32_16x16x32_bf16 v[70:73], v[222:225], v[162:165], v[70:73]
	v_mfma_f32_16x16x32_bf16 v[74:77], v[226:229], v[162:165], v[74:77]
	s_add_u32 m0, s6, 0x0
	s_nop 0
	global_load_lds_dwordx4 v136, s[0:1]
	v_mfma_f32_16x16x32_bf16 v[78:81], v[230:233], v[162:165], v[78:81]
	v_mfma_f32_16x16x32_bf16 v[82:85], v[218:221], v[166:169], v[82:85]
	v_mfma_f32_16x16x32_bf16 v[86:89], v[222:225], v[166:169], v[86:89]
	v_mfma_f32_16x16x32_bf16 v[90:93], v[226:229], v[166:169], v[90:93]
	s_add_u32 m0, s6, 0x2000
	s_nop 0
	global_load_lds_dwordx4 v137, s[0:1]
	v_mfma_f32_16x16x32_bf16 v[94:97], v[230:233], v[166:169], v[94:97]
	v_mfma_f32_16x16x32_bf16 v[98:101], v[218:221], v[170:173], v[98:101]
	v_mfma_f32_16x16x32_bf16 v[102:105], v[222:225], v[170:173], v[102:105]
	v_mfma_f32_16x16x32_bf16 v[106:109], v[226:229], v[170:173], v[106:109]
	s_add_u32 m0, s6, 0x4000
	s_nop 0
	global_load_lds_dwordx4 v136, s[2:3]
	v_mfma_f32_16x16x32_bf16 v[110:113], v[230:233], v[170:173], v[110:113]
	v_mfma_f32_16x16x32_bf16 v[114:117], v[218:221], v[174:177], v[114:117]
	v_mfma_f32_16x16x32_bf16 v[118:121], v[222:225], v[174:177], v[118:121]
	v_mfma_f32_16x16x32_bf16 v[122:125], v[226:229], v[174:177], v[122:125]
	s_add_u32 m0, s6, 0x6000
	s_nop 0
	global_load_lds_dwordx4 v137, s[2:3]
	v_mfma_f32_16x16x32_bf16 v[126:129], v[230:233], v[174:177], v[126:129]
	s_add_u32 s0, s0, 1024
	s_addc_u32 s1, s1, 0
	s_add_u32 s2, s2, 1024
	s_addc_u32 s3, s3, 0
	ds_read_b128 v[218:221], v140 offset:8192
	ds_read_b128 v[222:225], v140 offset:9216
	ds_read_b128 v[226:229], v140 offset:10240
	ds_read_b128 v[230:233], v140 offset:11264
	s_waitcnt lgkmcnt(4)
	v_mfma_f32_16x16x32_bf16 v[2:5], v[194:197], v[178:181], v[2:5]
	v_mfma_f32_16x16x32_bf16 v[6:9], v[198:201], v[178:181], v[6:9]
	v_mfma_f32_16x16x32_bf16 v[10:13], v[202:205], v[178:181], v[10:13]
	v_mfma_f32_16x16x32_bf16 v[14:17], v[206:209], v[178:181], v[14:17]
	v_mfma_f32_16x16x32_bf16 v[18:21], v[194:197], v[182:185], v[18:21]
	v_mfma_f32_16x16x32_bf16 v[22:25], v[198:201], v[182:185], v[22:25]
	v_mfma_f32_16x16x32_bf16 v[26:29], v[202:205], v[182:185], v[26:29]
	v_mfma_f32_16x16x32_bf16 v[30:33], v[206:209], v[182:185], v[30:33]
	v_mfma_f32_16x16x32_bf16 v[34:37], v[194:197], v[186:189], v[34:37]
	v_mfma_f32_16x16x32_bf16 v[38:41], v[198:201], v[186:189], v[38:41]
	v_mfma_f32_16x16x32_bf16 v[42:45], v[202:205], v[186:189], v[42:45]
	v_mfma_f32_16x16x32_bf16 v[46:49], v[206:209], v[186:189], v[46:49]
	v_mfma_f32_16x16x32_bf16 v[50:53], v[194:197], v[190:193], v[50:53]
	v_mfma_f32_16x16x32_bf16 v[54:57], v[198:201], v[190:193], v[54:57]
	v_mfma_f32_16x16x32_bf16 v[58:61], v[202:205], v[190:193], v[58:61]
	v_mfma_f32_16x16x32_bf16 v[62:65], v[206:209], v[190:193], v[62:65]
	s_waitcnt lgkmcnt(0)
	s_waitcnt vmcnt(8)
	s_barrier
	v_add_u32_e32 v139, 0x10000, v134
	v_add_u32_e32 v140, 0x10000, v135
	ds_read_b128 v[162:165], v139 offset:0
	ds_read_b128 v[166:169], v139 offset:1024
	ds_read_b128 v[170:173], v139 offset:2048
	ds_read_b128 v[174:177], v139 offset:3072
	ds_read_b128 v[194:197], v140 offset:0
	ds_read_b128 v[198:201], v140 offset:1024
	ds_read_b128 v[202:205], v140 offset:2048
	ds_read_b128 v[206:209], v140 offset:3072
	v_mfma_f32_16x16x32_bf16 v[66:69], v[218:221], v[178:181], v[66:69]
	v_mfma_f32_16x16x32_bf16 v[70:73], v[222:225], v[178:181], v[70:73]
	v_mfma_f32_16x16x32_bf16 v[74:77], v[226:229], v[178:181], v[74:77]
	s_add_u32 m0, s6, 0x8000
	s_nop 0
	global_load_lds_dwordx4 v136, s[0:1]
	v_mfma_f32_16x16x32_bf16 v[78:81], v[230:233], v[178:181], v[78:81]
	v_mfma_f32_16x16x32_bf16 v[82:85], v[218:221], v[182:185], v[82:85]
	v_mfma_f32_16x16x32_bf16 v[86:89], v[222:225], v[182:185], v[86:89]
	v_mfma_f32_16x16x32_bf16 v[90:93], v[226:229], v[182:185], v[90:93]
	s_add_u32 m0, s6, 0xa000
	s_nop 0
	global_load_lds_dwordx4 v137, s[0:1]
	v_mfma_f32_16x16x32_bf16 v[94:97], v[230:233], v[182:185], v[94:97]
	v_mfma_f32_16x16x32_bf16 v[98:101], v[218:221], v[186:189], v[98:101]
	v_mfma_f32_16x16x32_bf16 v[102:105], v[222:225], v[186:189], v[102:105]
	v_mfma_f32_16x16x32_bf16 v[106:109], v[226:229], v[186:189], v[106:109]
	s_add_u32 m0, s6, 0xc000
	s_nop 0
	global_load_lds_dwordx4 v136, s[2:3]
	v_mfma_f32_16x16x32_bf16 v[110:113], v[230:233], v[186:189], v[110:113]
	v_mfma_f32_16x16x32_bf16 v[114:117], v[218:221], v[190:193], v[114:117]
	v_mfma_f32_16x16x32_bf16 v[118:121], v[222:225], v[190:193], v[118:121]
	v_mfma_f32_16x16x32_bf16 v[122:125], v[226:229], v[190:193], v[122:125]
	s_add_u32 m0, s6, 0xe000
	s_nop 0
	global_load_lds_dwordx4 v137, s[2:3]
	v_mfma_f32_16x16x32_bf16 v[126:129], v[230:233], v[190:193], v[126:129]
	s_add_u32 s0, s0, 1024
	s_addc_u32 s1, s1, 0
	s_add_u32 s2, s2, 1024
	s_addc_u32 s3, s3, 0
	ds_read_b128 v[218:221], v140 offset:8192
	ds_read_b128 v[222:225], v140 offset:9216
	ds_read_b128 v[226:229], v140 offset:10240
	ds_read_b128 v[230:233], v140 offset:11264
	s_waitcnt lgkmcnt(4)
	v_mfma_f32_16x16x32_bf16 v[2:5], v[194:197], v[162:165], v[2:5]
	v_mfma_f32_16x16x32_bf16 v[6:9], v[198:201], v[162:165], v[6:9]
	v_mfma_f32_16x16x32_bf16 v[10:13], v[202:205], v[162:165], v[10:13]
	v_mfma_f32_16x16x32_bf16 v[14:17], v[206:209], v[162:165], v[14:17]
	v_mfma_f32_16x16x32_bf16 v[18:21], v[194:197], v[166:169], v[18:21]
	v_mfma_f32_16x16x32_bf16 v[22:25], v[198:201], v[166:169], v[22:25]
	v_mfma_f32_16x16x32_bf16 v[26:29], v[202:205], v[166:169], v[26:29]
	v_mfma_f32_16x16x32_bf16 v[30:33], v[206:209], v[166:169], v[30:33]
	v_mfma_f32_16x16x32_bf16 v[34:37], v[194:197], v[170:173], v[34:37]
	v_mfma_f32_16x16x32_bf16 v[38:41], v[198:201], v[170:173], v[38:41]
	v_mfma_f32_16x16x32_bf16 v[42:45], v[202:205], v[170:173], v[42:45]
	v_mfma_f32_16x16x32_bf16 v[46:49], v[206:209], v[170:173], v[46:49]
	v_mfma_f32_16x16x32_bf16 v[50:53], v[194:197], v[174:177], v[50:53]
	v_mfma_f32_16x16x32_bf16 v[54:57], v[198:201], v[174:177], v[54:57]
	v_mfma_f32_16x16x32_bf16 v[58:61], v[202:205], v[174:177], v[58:61]
	v_mfma_f32_16x16x32_bf16 v[62:65], v[206:209], v[174:177], v[62:65]
	s_waitcnt lgkmcnt(0)
	s_waitcnt vmcnt(8)
	s_barrier
	v_add_u32_e32 v139, 0x18000, v134
	v_add_u32_e32 v140, 0x18000, v135
	ds_read_b128 v[178:181], v139 offset:0
	ds_read_b128 v[182:185], v139 offset:1024
	ds_read_b128 v[186:189], v139 offset:2048
	ds_read_b128 v[190:193], v139 offset:3072
	ds_read_b128 v[194:197], v140 offset:0
	ds_read_b128 v[198:201], v140 offset:1024
	ds_read_b128 v[202:205], v140 offset:2048
	ds_read_b128 v[206:209], v140 offset:3072
	v_mfma_f32_16x16x32_bf16 v[66:69], v[218:221], v[162:165], v[66:69]
	v_mfma_f32_16x16x32_bf16 v[70:73], v[222:225], v[162:165], v[70:73]
	v_mfma_f32_16x16x32_bf16 v[74:77], v[226:229], v[162:165], v[74:77]
	s_add_u32 m0, s6, 0x10000
	s_nop 0
	global_load_lds_dwordx4 v136, s[0:1]
	v_mfma_f32_16x16x32_bf16 v[78:81], v[230:233], v[162:165], v[78:81]
	v_mfma_f32_16x16x32_bf16 v[82:85], v[218:221], v[166:169], v[82:85]
	v_mfma_f32_16x16x32_bf16 v[86:89], v[222:225], v[166:169], v[86:89]
	v_mfma_f32_16x16x32_bf16 v[90:93], v[226:229], v[166:169], v[90:93]
	s_add_u32 m0, s6, 0x12000
	s_nop 0
	global_load_lds_dwordx4 v137, s[0:1]
	v_mfma_f32_16x16x32_bf16 v[94:97], v[230:233], v[166:169], v[94:97]
	v_mfma_f32_16x16x32_bf16 v[98:101], v[218:221], v[170:173], v[98:101]
	v_mfma_f32_16x16x32_bf16 v[102:105], v[222:225], v[170:173], v[102:105]
	v_mfma_f32_16x16x32_bf16 v[106:109], v[226:229], v[170:173], v[106:109]
	s_add_u32 m0, s6, 0x14000
	s_nop 0
	global_load_lds_dwordx4 v136, s[2:3]
	v_mfma_f32_16x16x32_bf16 v[110:113], v[230:233], v[170:173], v[110:113]
	v_mfma_f32_16x16x32_bf16 v[114:117], v[218:221], v[174:177], v[114:117]
	v_mfma_f32_16x16x32_bf16 v[118:121], v[222:225], v[174:177], v[118:121]
	v_mfma_f32_16x16x32_bf16 v[122:125], v[226:229], v[174:177], v[122:125]
	s_add_u32 m0, s6, 0x16000
	s_nop 0
	global_load_lds_dwordx4 v137, s[2:3]
	v_mfma_f32_16x16x32_bf16 v[126:129], v[230:233], v[174:177], v[126:129]
	s_add_u32 s0, s0, 1024
	s_addc_u32 s1, s1, 0
	s_add_u32 s2, s2, 1024
	s_addc_u32 s3, s3, 0
	ds_read_b128 v[218:221], v140 offset:8192
	ds_read_b128 v[222:225], v140 offset:9216
	ds_read_b128 v[226:229], v140 offset:10240
	ds_read_b128 v[230:233], v140 offset:11264
	s_waitcnt lgkmcnt(4)
	v_mfma_f32_16x16x32_bf16 v[2:5], v[194:197], v[178:181], v[2:5]
	v_mfma_f32_16x16x32_bf16 v[6:9], v[198:201], v[178:181], v[6:9]
	v_mfma_f32_16x16x32_bf16 v[10:13], v[202:205], v[178:181], v[10:13]
	v_mfma_f32_16x16x32_bf16 v[14:17], v[206:209], v[178:181], v[14:17]
	v_mfma_f32_16x16x32_bf16 v[18:21], v[194:197], v[182:185], v[18:21]
	v_mfma_f32_16x16x32_bf16 v[22:25], v[198:201], v[182:185], v[22:25]
	v_mfma_f32_16x16x32_bf16 v[26:29], v[202:205], v[182:185], v[26:29]
	v_mfma_f32_16x16x32_bf16 v[30:33], v[206:209], v[182:185], v[30:33]
	v_mfma_f32_16x16x32_bf16 v[34:37], v[194:197], v[186:189], v[34:37]
	v_mfma_f32_16x16x32_bf16 v[38:41], v[198:201], v[186:189], v[38:41]
	v_mfma_f32_16x16x32_bf16 v[42:45], v[202:205], v[186:189], v[42:45]
	v_mfma_f32_16x16x32_bf16 v[46:49], v[206:209], v[186:189], v[46:49]
	v_mfma_f32_16x16x32_bf16 v[50:53], v[194:197], v[190:193], v[50:53]
	v_mfma_f32_16x16x32_bf16 v[54:57], v[198:201], v[190:193], v[54:57]
	v_mfma_f32_16x16x32_bf16 v[58:61], v[202:205], v[190:193], v[58:61]
	v_mfma_f32_16x16x32_bf16 v[62:65], v[206:209], v[190:193], v[62:65]
	s_waitcnt lgkmcnt(0)
	s_sub_u32 s7, s7, 1
	s_cmp_lg_u32 s7, 0
	s_cbranch_scc1 .Lg2_a_klB4
	s_waitcnt vmcnt(8)
	s_barrier
	v_add_u32_e32 v139, 0x0, v134
	v_add_u32_e32 v140, 0x0, v135
	ds_read_b128 v[162:165], v139 offset:0
	ds_read_b128 v[166:169], v139 offset:1024
	ds_read_b128 v[170:173], v139 offset:2048
	ds_read_b128 v[174:177], v139 offset:3072
	ds_read_b128 v[194:197], v140 offset:0
	ds_read_b128 v[198:201], v140 offset:1024
	ds_read_b128 v[202:205], v140 offset:2048
	ds_read_b128 v[206:209], v140 offset:3072
	v_mfma_f32_16x16x32_bf16 v[66:69], v[218:221], v[178:181], v[66:69]
	v_mfma_f32_16x16x32_bf16 v[70:73], v[222:225], v[178:181], v[70:73]
	v_mfma_f32_16x16x32_bf16 v[74:77], v[226:229], v[178:181], v[74:77]
	s_add_u32 m0, s6, 0x18000
	s_nop 0
	global_load_lds_dwordx4 v136, s[0:1]
	v_mfma_f32_16x16x32_bf16 v[78:81], v[230:233], v[178:181], v[78:81]
	v_mfma_f32_16x16x32_bf16 v[82:85], v[218:221], v[182:185], v[82:85]
	v_mfma_f32_16x16x32_bf16 v[86:89], v[222:225], v[182:185], v[86:89]
	v_mfma_f32_16x16x32_bf16 v[90:93], v[226:229], v[182:185], v[90:93]
	s_add_u32 m0, s6, 0x1a000
	s_nop 0
	global_load_lds_dwordx4 v137, s[0:1]
	v_mfma_f32_16x16x32_bf16 v[94:97], v[230:233], v[182:185], v[94:97]
	v_mfma_f32_16x16x32_bf16 v[98:101], v[218:221], v[186:189], v[98:101]
	v_mfma_f32_16x16x32_bf16 v[102:105], v[222:225], v[186:189], v[102:105]
	v_mfma_f32_16x16x32_bf16 v[106:109], v[226:229], v[186:189], v[106:109]
	s_add_u32 m0, s6, 0x1c000
	s_nop 0
	global_load_lds_dwordx4 v136, s[2:3]
	v_mfma_f32_16x16x32_bf16 v[110:113], v[230:233], v[186:189], v[110:113]
	v_mfma_f32_16x16x32_bf16 v[114:117], v[218:221], v[190:193], v[114:117]
	v_mfma_f32_16x16x32_bf16 v[118:121], v[222:225], v[190:193], v[118:121]
	v_mfma_f32_16x16x32_bf16 v[122:125], v[226:229], v[190:193], v[122:125]
	s_add_u32 m0, s6, 0x1e000
	s_nop 0
	global_load_lds_dwordx4 v137, s[2:3]
	v_mfma_f32_16x16x32_bf16 v[126:129], v[230:233], v[190:193], v[126:129]
	s_add_u32 s0, s0, 1024
	s_addc_u32 s1, s1, 0
	s_add_u32 s2, s2, 1024
	s_addc_u32 s3, s3, 0
	ds_read_b128 v[218:221], v140 offset:8192
	ds_read_b128 v[222:225], v140 offset:9216
	ds_read_b128 v[226:229], v140 offset:10240
	ds_read_b128 v[230:233], v140 offset:11264
	s_waitcnt lgkmcnt(4)
	v_mfma_f32_16x16x32_bf16 v[2:5], v[194:197], v[162:165], v[2:5]
	v_mfma_f32_16x16x32_bf16 v[6:9], v[198:201], v[162:165], v[6:9]
	v_mfma_f32_16x16x32_bf16 v[10:13], v[202:205], v[162:165], v[10:13]
	v_mfma_f32_16x16x32_bf16 v[14:17], v[206:209], v[162:165], v[14:17]
	v_mfma_f32_16x16x32_bf16 v[18:21], v[194:197], v[166:169], v[18:21]
	v_mfma_f32_16x16x32_bf16 v[22:25], v[198:201], v[166:169], v[22:25]
	v_mfma_f32_16x16x32_bf16 v[26:29], v[202:205], v[166:169], v[26:29]
	v_mfma_f32_16x16x32_bf16 v[30:33], v[206:209], v[166:169], v[30:33]
	v_mfma_f32_16x16x32_bf16 v[34:37], v[194:197], v[170:173], v[34:37]
	v_mfma_f32_16x16x32_bf16 v[38:41], v[198:201], v[170:173], v[38:41]
	v_mfma_f32_16x16x32_bf16 v[42:45], v[202:205], v[170:173], v[42:45]
	v_mfma_f32_16x16x32_bf16 v[46:49], v[206:209], v[170:173], v[46:49]
	v_mfma_f32_16x16x32_bf16 v[50:53], v[194:197], v[174:177], v[50:53]
	v_mfma_f32_16x16x32_bf16 v[54:57], v[198:201], v[174:177], v[54:57]
	v_mfma_f32_16x16x32_bf16 v[58:61], v[202:205], v[174:177], v[58:61]
	v_mfma_f32_16x16x32_bf16 v[62:65], v[206:209], v[174:177], v[62:65]
	s_waitcnt lgkmcnt(0)
	s_waitcnt vmcnt(8)
	s_barrier
	v_add_u32_e32 v139, 0x8000, v134
	v_add_u32_e32 v140, 0x8000, v135
	ds_read_b128 v[178:181], v139 offset:0
	ds_read_b128 v[182:185], v139 offset:1024
	ds_read_b128 v[186:189], v139 offset:2048
	ds_read_b128 v[190:193], v139 offset:3072
	ds_read_b128 v[194:197], v140 offset:0
	ds_read_b128 v[198:201], v140 offset:1024
	ds_read_b128 v[202:205], v140 offset:2048
	ds_read_b128 v[206:209], v140 offset:3072
	v_mfma_f32_16x16x32_bf16 v[66:69], v[218:221], v[162:165], v[66:69]
	v_mfma_f32_16x16x32_bf16 v[70:73], v[222:225], v[162:165], v[70:73]
	v_mfma_f32_16x16x32_bf16 v[74:77], v[226:229], v[162:165], v[74:77]
	v_mfma_f32_16x16x32_bf16 v[78:81], v[230:233], v[162:165], v[78:81]
	v_mfma_f32_16x16x32_bf16 v[82:85], v[218:221], v[166:169], v[82:85]
	v_mfma_f32_16x16x32_bf16 v[86:89], v[222:225], v[166:169], v[86:89]
	v_mfma_f32_16x16x32_bf16 v[90:93], v[226:229], v[166:169], v[90:93]
	v_mfma_f32_16x16x32_bf16 v[94:97], v[230:233], v[166:169], v[94:97]
	v_mfma_f32_16x16x32_bf16 v[98:101], v[218:221], v[170:173], v[98:101]
	v_mfma_f32_16x16x32_bf16 v[102:105], v[222:225], v[170:173], v[102:105]
	v_mfma_f32_16x16x32_bf16 v[106:109], v[226:229], v[170:173], v[106:109]
	v_mfma_f32_16x16x32_bf16 v[110:113], v[230:233], v[170:173], v[110:113]
	v_mfma_f32_16x16x32_bf16 v[114:117], v[218:221], v[174:177], v[114:117]
	v_mfma_f32_16x16x32_bf16 v[118:121], v[222:225], v[174:177], v[118:121]
	v_mfma_f32_16x16x32_bf16 v[122:125], v[226:229], v[174:177], v[122:125]
	v_mfma_f32_16x16x32_bf16 v[126:129], v[230:233], v[174:177], v[126:129]
	ds_read_b128 v[218:221], v140 offset:8192
	ds_read_b128 v[222:225], v140 offset:9216
	ds_read_b128 v[226:229], v140 offset:10240
	ds_read_b128 v[230:233], v140 offset:11264
	s_waitcnt lgkmcnt(4)
	v_mfma_f32_16x16x32_bf16 v[2:5], v[194:197], v[178:181], v[2:5]
	v_mfma_f32_16x16x32_bf16 v[6:9], v[198:201], v[178:181], v[6:9]
	v_mfma_f32_16x16x32_bf16 v[10:13], v[202:205], v[178:181], v[10:13]
	v_mfma_f32_16x16x32_bf16 v[14:17], v[206:209], v[178:181], v[14:17]
	v_mfma_f32_16x16x32_bf16 v[18:21], v[194:197], v[182:185], v[18:21]
	v_mfma_f32_16x16x32_bf16 v[22:25], v[198:201], v[182:185], v[22:25]
	v_mfma_f32_16x16x32_bf16 v[26:29], v[202:205], v[182:185], v[26:29]
	v_mfma_f32_16x16x32_bf16 v[30:33], v[206:209], v[182:185], v[30:33]
	v_mfma_f32_16x16x32_bf16 v[34:37], v[194:197], v[186:189], v[34:37]
	v_mfma_f32_16x16x32_bf16 v[38:41], v[198:201], v[186:189], v[38:41]
	v_mfma_f32_16x16x32_bf16 v[42:45], v[202:205], v[186:189], v[42:45]
	v_mfma_f32_16x16x32_bf16 v[46:49], v[206:209], v[186:189], v[46:49]
	v_mfma_f32_16x16x32_bf16 v[50:53], v[194:197], v[190:193], v[50:53]
	v_mfma_f32_16x16x32_bf16 v[54:57], v[198:201], v[190:193], v[54:57]
	v_mfma_f32_16x16x32_bf16 v[58:61], v[202:205], v[190:193], v[58:61]
	v_mfma_f32_16x16x32_bf16 v[62:65], v[206:209], v[190:193], v[62:65]
	s_waitcnt lgkmcnt(0)
	s_waitcnt vmcnt(4)
	s_barrier
	v_add_u32_e32 v139, 0x10000, v134
	v_add_u32_e32 v140, 0x10000, v135
	ds_read_b128 v[162:165], v139 offset:0
	ds_read_b128 v[166:169], v139 offset:1024
	ds_read_b128 v[170:173], v139 offset:2048
	ds_read_b128 v[174:177], v139 offset:3072
	ds_read_b128 v[194:197], v140 offset:0
	ds_read_b128 v[198:201], v140 offset:1024
	ds_read_b128 v[202:205], v140 offset:2048
	ds_read_b128 v[206:209], v140 offset:3072
	v_mfma_f32_16x16x32_bf16 v[66:69], v[218:221], v[178:181], v[66:69]
	v_mfma_f32_16x16x32_bf16 v[70:73], v[222:225], v[178:181], v[70:73]
	v_mfma_f32_16x16x32_bf16 v[74:77], v[226:229], v[178:181], v[74:77]
	v_mfma_f32_16x16x32_bf16 v[78:81], v[230:233], v[178:181], v[78:81]
	v_mfma_f32_16x16x32_bf16 v[82:85], v[218:221], v[182:185], v[82:85]
	v_mfma_f32_16x16x32_bf16 v[86:89], v[222:225], v[182:185], v[86:89]
	v_mfma_f32_16x16x32_bf16 v[90:93], v[226:229], v[182:185], v[90:93]
	v_mfma_f32_16x16x32_bf16 v[94:97], v[230:233], v[182:185], v[94:97]
	v_mfma_f32_16x16x32_bf16 v[98:101], v[218:221], v[186:189], v[98:101]
	v_mfma_f32_16x16x32_bf16 v[102:105], v[222:225], v[186:189], v[102:105]
	v_mfma_f32_16x16x32_bf16 v[106:109], v[226:229], v[186:189], v[106:109]
	v_mfma_f32_16x16x32_bf16 v[110:113], v[230:233], v[186:189], v[110:113]
	v_mfma_f32_16x16x32_bf16 v[114:117], v[218:221], v[190:193], v[114:117]
	v_mfma_f32_16x16x32_bf16 v[118:121], v[222:225], v[190:193], v[118:121]
	v_mfma_f32_16x16x32_bf16 v[122:125], v[226:229], v[190:193], v[122:125]
	v_mfma_f32_16x16x32_bf16 v[126:129], v[230:233], v[190:193], v[126:129]
	ds_read_b128 v[218:221], v140 offset:8192
	ds_read_b128 v[222:225], v140 offset:9216
	ds_read_b128 v[226:229], v140 offset:10240
	ds_read_b128 v[230:233], v140 offset:11264
	s_waitcnt lgkmcnt(4)
	v_mfma_f32_16x16x32_bf16 v[2:5], v[194:197], v[162:165], v[2:5]
	v_mfma_f32_16x16x32_bf16 v[6:9], v[198:201], v[162:165], v[6:9]
	v_mfma_f32_16x16x32_bf16 v[10:13], v[202:205], v[162:165], v[10:13]
	v_mfma_f32_16x16x32_bf16 v[14:17], v[206:209], v[162:165], v[14:17]
	v_mfma_f32_16x16x32_bf16 v[18:21], v[194:197], v[166:169], v[18:21]
	v_mfma_f32_16x16x32_bf16 v[22:25], v[198:201], v[166:169], v[22:25]
	v_mfma_f32_16x16x32_bf16 v[26:29], v[202:205], v[166:169], v[26:29]
	v_mfma_f32_16x16x32_bf16 v[30:33], v[206:209], v[166:169], v[30:33]
	v_mfma_f32_16x16x32_bf16 v[34:37], v[194:197], v[170:173], v[34:37]
	v_mfma_f32_16x16x32_bf16 v[38:41], v[198:201], v[170:173], v[38:41]
	v_mfma_f32_16x16x32_bf16 v[42:45], v[202:205], v[170:173], v[42:45]
	v_mfma_f32_16x16x32_bf16 v[46:49], v[206:209], v[170:173], v[46:49]
	v_mfma_f32_16x16x32_bf16 v[50:53], v[194:197], v[174:177], v[50:53]
	v_mfma_f32_16x16x32_bf16 v[54:57], v[198:201], v[174:177], v[54:57]
	v_mfma_f32_16x16x32_bf16 v[58:61], v[202:205], v[174:177], v[58:61]
	v_mfma_f32_16x16x32_bf16 v[62:65], v[206:209], v[174:177], v[62:65]
	s_waitcnt lgkmcnt(0)
	s_waitcnt vmcnt(0)
	s_barrier
	v_add_u32_e32 v139, 0x18000, v134
	v_add_u32_e32 v140, 0x18000, v135
	ds_read_b128 v[178:181], v139 offset:0
	ds_read_b128 v[182:185], v139 offset:1024
	ds_read_b128 v[186:189], v139 offset:2048
	ds_read_b128 v[190:193], v139 offset:3072
	ds_read_b128 v[194:197], v140 offset:0
	ds_read_b128 v[198:201], v140 offset:1024
	ds_read_b128 v[202:205], v140 offset:2048
	ds_read_b128 v[206:209], v140 offset:3072
	v_mfma_f32_16x16x32_bf16 v[66:69], v[218:221], v[162:165], v[66:69]
	v_mfma_f32_16x16x32_bf16 v[70:73], v[222:225], v[162:165], v[70:73]
	v_mfma_f32_16x16x32_bf16 v[74:77], v[226:229], v[162:165], v[74:77]
	v_mfma_f32_16x16x32_bf16 v[78:81], v[230:233], v[162:165], v[78:81]
	v_mfma_f32_16x16x32_bf16 v[82:85], v[218:221], v[166:169], v[82:85]
	v_mfma_f32_16x16x32_bf16 v[86:89], v[222:225], v[166:169], v[86:89]
	v_mfma_f32_16x16x32_bf16 v[90:93], v[226:229], v[166:169], v[90:93]
	v_mfma_f32_16x16x32_bf16 v[94:97], v[230:233], v[166:169], v[94:97]
	v_mfma_f32_16x16x32_bf16 v[98:101], v[218:221], v[170:173], v[98:101]
	v_mfma_f32_16x16x32_bf16 v[102:105], v[222:225], v[170:173], v[102:105]
	v_mfma_f32_16x16x32_bf16 v[106:109], v[226:229], v[170:173], v[106:109]
	v_mfma_f32_16x16x32_bf16 v[110:113], v[230:233], v[170:173], v[110:113]
	v_mfma_f32_16x16x32_bf16 v[114:117], v[218:221], v[174:177], v[114:117]
	v_mfma_f32_16x16x32_bf16 v[118:121], v[222:225], v[174:177], v[118:121]
	v_mfma_f32_16x16x32_bf16 v[122:125], v[226:229], v[174:177], v[122:125]
	v_mfma_f32_16x16x32_bf16 v[126:129], v[230:233], v[174:177], v[126:129]
	ds_read_b128 v[218:221], v140 offset:8192
	ds_read_b128 v[222:225], v140 offset:9216
	ds_read_b128 v[226:229], v140 offset:10240
	ds_read_b128 v[230:233], v140 offset:11264
	s_waitcnt lgkmcnt(4)
	v_mfma_f32_16x16x32_bf16 v[2:5], v[194:197], v[178:181], v[2:5]
	v_mfma_f32_16x16x32_bf16 v[6:9], v[198:201], v[178:181], v[6:9]
	v_mfma_f32_16x16x32_bf16 v[10:13], v[202:205], v[178:181], v[10:13]
	v_mfma_f32_16x16x32_bf16 v[14:17], v[206:209], v[178:181], v[14:17]
	v_mfma_f32_16x16x32_bf16 v[18:21], v[194:197], v[182:185], v[18:21]
	v_mfma_f32_16x16x32_bf16 v[22:25], v[198:201], v[182:185], v[22:25]
	v_mfma_f32_16x16x32_bf16 v[26:29], v[202:205], v[182:185], v[26:29]
	v_mfma_f32_16x16x32_bf16 v[30:33], v[206:209], v[182:185], v[30:33]
	v_mfma_f32_16x16x32_bf16 v[34:37], v[194:197], v[186:189], v[34:37]
	v_mfma_f32_16x16x32_bf16 v[38:41], v[198:201], v[186:189], v[38:41]
	v_mfma_f32_16x16x32_bf16 v[42:45], v[202:205], v[186:189], v[42:45]
	v_mfma_f32_16x16x32_bf16 v[46:49], v[206:209], v[186:189], v[46:49]
	v_mfma_f32_16x16x32_bf16 v[50:53], v[194:197], v[190:193], v[50:53]
	v_mfma_f32_16x16x32_bf16 v[54:57], v[198:201], v[190:193], v[54:57]
	v_mfma_f32_16x16x32_bf16 v[58:61], v[202:205], v[190:193], v[58:61]
	v_mfma_f32_16x16x32_bf16 v[62:65], v[206:209], v[190:193], v[62:65]
	s_waitcnt lgkmcnt(0)
	v_mfma_f32_16x16x32_bf16 v[66:69], v[218:221], v[178:181], v[66:69]
	v_mfma_f32_16x16x32_bf16 v[70:73], v[222:225], v[178:181], v[70:73]
	v_mfma_f32_16x16x32_bf16 v[74:77], v[226:229], v[178:181], v[74:77]
	v_mfma_f32_16x16x32_bf16 v[78:81], v[230:233], v[178:181], v[78:81]
	v_mfma_f32_16x16x32_bf16 v[82:85], v[218:221], v[182:185], v[82:85]
	v_mfma_f32_16x16x32_bf16 v[86:89], v[222:225], v[182:185], v[86:89]
	v_mfma_f32_16x16x32_bf16 v[90:93], v[226:229], v[182:185], v[90:93]
	v_mfma_f32_16x16x32_bf16 v[94:97], v[230:233], v[182:185], v[94:97]
	v_mfma_f32_16x16x32_bf16 v[98:101], v[218:221], v[186:189], v[98:101]
	v_mfma_f32_16x16x32_bf16 v[102:105], v[222:225], v[186:189], v[102:105]
	v_mfma_f32_16x16x32_bf16 v[106:109], v[226:229], v[186:189], v[106:109]
	v_mfma_f32_16x16x32_bf16 v[110:113], v[230:233], v[186:189], v[110:113]
	v_mfma_f32_16x16x32_bf16 v[114:117], v[218:221], v[190:193], v[114:117]
	v_mfma_f32_16x16x32_bf16 v[118:121], v[222:225], v[190:193], v[118:121]
	v_mfma_f32_16x16x32_bf16 v[122:125], v[226:229], v[190:193], v[122:125]
	v_mfma_f32_16x16x32_bf16 v[126:129], v[230:233], v[190:193], v[126:129]
.Lg2_a_kdone3:
	s_nop 7
	s_nop 1
	v_mov_b32_e32 v176, v138
	v_mul_f32_e32 v162, 0xbfb8aa3b, v2
	v_mul_f32_e32 v163, 0xbfb8aa3b, v3
	v_mul_f32_e32 v164, 0xbfb8aa3b, v4
	v_mul_f32_e32 v165, 0xbfb8aa3b, v5
	v_exp_f32_e32 v162, v162
	v_exp_f32_e32 v163, v163
	v_exp_f32_e32 v164, v164
	v_exp_f32_e32 v165, v165
	v_add_f32_e32 v162, 1.0, v162
	v_add_f32_e32 v163, 1.0, v163
	v_add_f32_e32 v164, 1.0, v164
	v_add_f32_e32 v165, 1.0, v165
	v_rcp_f32_e32 v162, v162
	v_rcp_f32_e32 v163, v163
	v_rcp_f32_e32 v164, v164
	v_rcp_f32_e32 v165, v165
	v_mul_f32_e32 v162, v2, v162
	v_mul_f32_e32 v163, v3, v163
	v_mul_f32_e32 v164, v4, v164
	v_mul_f32_e32 v165, v5, v165
	v_mul_f32_e32 v162, v10, v162
	v_mul_f32_e32 v163, v11, v163
	v_mul_f32_e32 v164, v12, v164
	v_mul_f32_e32 v165, v13, v165
	v_cvt_pk_bf16_f32 v168, v162, v163
	v_cvt_pk_bf16_f32 v169, v164, v165
	v_mul_f32_e32 v162, 0xbfb8aa3b, v6
	v_mul_f32_e32 v163, 0xbfb8aa3b, v7
	v_mul_f32_e32 v164, 0xbfb8aa3b, v8
	v_mul_f32_e32 v165, 0xbfb8aa3b, v9
	v_exp_f32_e32 v162, v162
	v_exp_f32_e32 v163, v163
	v_exp_f32_e32 v164, v164
	v_exp_f32_e32 v165, v165
	v_add_f32_e32 v162, 1.0, v162
	v_add_f32_e32 v163, 1.0, v163
	v_add_f32_e32 v164, 1.0, v164
	v_add_f32_e32 v165, 1.0, v165
	v_rcp_f32_e32 v162, v162
	v_rcp_f32_e32 v163, v163
	v_rcp_f32_e32 v164, v164
	v_rcp_f32_e32 v165, v165
	v_mul_f32_e32 v162, v6, v162
	v_mul_f32_e32 v163, v7, v163
	v_mul_f32_e32 v164, v8, v164
	v_mul_f32_e32 v165, v9, v165
	v_mul_f32_e32 v162, v14, v162
	v_mul_f32_e32 v163, v15, v163
	v_mul_f32_e32 v164, v16, v164
	v_mul_f32_e32 v165, v17, v165
	v_cvt_pk_bf16_f32 v170, v162, v163
	v_cvt_pk_bf16_f32 v171, v164, v165
	s_nop 1
	v_permlane16_swap_b32_e32 v168, v170
	v_permlane16_swap_b32_e32 v169, v171
	global_store_dwordx4 v176, v[168:171], s[4:5] offset:0 sc1
	v_mul_f32_e32 v162, 0xbfb8aa3b, v66
	v_mul_f32_e32 v163, 0xbfb8aa3b, v67
	v_mul_f32_e32 v164, 0xbfb8aa3b, v68
	v_mul_f32_e32 v165, 0xbfb8aa3b, v69
	v_exp_f32_e32 v162, v162
	v_exp_f32_e32 v163, v163
	v_exp_f32_e32 v164, v164
	v_exp_f32_e32 v165, v165
	v_add_f32_e32 v162, 1.0, v162
	v_add_f32_e32 v163, 1.0, v163
	v_add_f32_e32 v164, 1.0, v164
	v_add_f32_e32 v165, 1.0, v165
	v_rcp_f32_e32 v162, v162
	v_rcp_f32_e32 v163, v163
	v_rcp_f32_e32 v164, v164
	v_rcp_f32_e32 v165, v165
	v_mul_f32_e32 v162, v66, v162
	v_mul_f32_e32 v163, v67, v163
	v_mul_f32_e32 v164, v68, v164
	v_mul_f32_e32 v165, v69, v165
	v_mul_f32_e32 v162, v74, v162
	v_mul_f32_e32 v163, v75, v163
	v_mul_f32_e32 v164, v76, v164
	v_mul_f32_e32 v165, v77, v165
	v_cvt_pk_bf16_f32 v172, v162, v163
	v_cvt_pk_bf16_f32 v173, v164, v165
	v_mul_f32_e32 v162, 0xbfb8aa3b, v70
	v_mul_f32_e32 v163, 0xbfb8aa3b, v71
	v_mul_f32_e32 v164, 0xbfb8aa3b, v72
	v_mul_f32_e32 v165, 0xbfb8aa3b, v73
	v_exp_f32_e32 v162, v162
	v_exp_f32_e32 v163, v163
	v_exp_f32_e32 v164, v164
	v_exp_f32_e32 v165, v165
	v_add_f32_e32 v162, 1.0, v162
	v_add_f32_e32 v163, 1.0, v163
	v_add_f32_e32 v164, 1.0, v164
	v_add_f32_e32 v165, 1.0, v165
	v_rcp_f32_e32 v162, v162
	v_rcp_f32_e32 v163, v163
	v_rcp_f32_e32 v164, v164
	v_rcp_f32_e32 v165, v165
	v_mul_f32_e32 v162, v70, v162
	v_mul_f32_e32 v163, v71, v163
	v_mul_f32_e32 v164, v72, v164
	v_mul_f32_e32 v165, v73, v165
	v_mul_f32_e32 v162, v78, v162
	v_mul_f32_e32 v163, v79, v163
	v_mul_f32_e32 v164, v80, v164
	v_mul_f32_e32 v165, v81, v165
	v_cvt_pk_bf16_f32 v174, v162, v163
	v_cvt_pk_bf16_f32 v175, v164, v165
	s_nop 1
	v_permlane16_swap_b32_e32 v172, v174
	v_permlane16_swap_b32_e32 v173, v175
	global_store_dwordx4 v176, v[172:175], s[4:5] offset:128 sc1
	v_add_u32_e32 v176, 0x16000, v176
	v_mul_f32_e32 v162, 0xbfb8aa3b, v18
	v_mul_f32_e32 v163, 0xbfb8aa3b, v19
	v_mul_f32_e32 v164, 0xbfb8aa3b, v20
	v_mul_f32_e32 v165, 0xbfb8aa3b, v21
	v_exp_f32_e32 v162, v162
	v_exp_f32_e32 v163, v163
	v_exp_f32_e32 v164, v164
	v_exp_f32_e32 v165, v165
	v_add_f32_e32 v162, 1.0, v162
	v_add_f32_e32 v163, 1.0, v163
	v_add_f32_e32 v164, 1.0, v164
	v_add_f32_e32 v165, 1.0, v165
	v_rcp_f32_e32 v162, v162
	v_rcp_f32_e32 v163, v163
	v_rcp_f32_e32 v164, v164
	v_rcp_f32_e32 v165, v165
	v_mul_f32_e32 v162, v18, v162
	v_mul_f32_e32 v163, v19, v163
	v_mul_f32_e32 v164, v20, v164
	v_mul_f32_e32 v165, v21, v165
	v_mul_f32_e32 v162, v26, v162
	v_mul_f32_e32 v163, v27, v163
	v_mul_f32_e32 v164, v28, v164
	v_mul_f32_e32 v165, v29, v165
	v_cvt_pk_bf16_f32 v168, v162, v163
	v_cvt_pk_bf16_f32 v169, v164, v165
	v_mul_f32_e32 v162, 0xbfb8aa3b, v22
	v_mul_f32_e32 v163, 0xbfb8aa3b, v23
	v_mul_f32_e32 v164, 0xbfb8aa3b, v24
	v_mul_f32_e32 v165, 0xbfb8aa3b, v25
	v_exp_f32_e32 v162, v162
	v_exp_f32_e32 v163, v163
	v_exp_f32_e32 v164, v164
	v_exp_f32_e32 v165, v165
	v_add_f32_e32 v162, 1.0, v162
	v_add_f32_e32 v163, 1.0, v163
	v_add_f32_e32 v164, 1.0, v164
	v_add_f32_e32 v165, 1.0, v165
	v_rcp_f32_e32 v162, v162
	v_rcp_f32_e32 v163, v163
	v_rcp_f32_e32 v164, v164
	v_rcp_f32_e32 v165, v165
	v_mul_f32_e32 v162, v22, v162
	v_mul_f32_e32 v163, v23, v163
	v_mul_f32_e32 v164, v24, v164
	v_mul_f32_e32 v165, v25, v165
	v_mul_f32_e32 v162, v30, v162
	v_mul_f32_e32 v163, v31, v163
	v_mul_f32_e32 v164, v32, v164
	v_mul_f32_e32 v165, v33, v165
	v_cvt_pk_bf16_f32 v170, v162, v163
	v_cvt_pk_bf16_f32 v171, v164, v165
	s_nop 1
	v_permlane16_swap_b32_e32 v168, v170
	v_permlane16_swap_b32_e32 v169, v171
	global_store_dwordx4 v176, v[168:171], s[4:5] offset:0 sc1
	v_mul_f32_e32 v162, 0xbfb8aa3b, v82
	v_mul_f32_e32 v163, 0xbfb8aa3b, v83
	v_mul_f32_e32 v164, 0xbfb8aa3b, v84
	v_mul_f32_e32 v165, 0xbfb8aa3b, v85
	v_exp_f32_e32 v162, v162
	v_exp_f32_e32 v163, v163
	v_exp_f32_e32 v164, v164
	v_exp_f32_e32 v165, v165
	v_add_f32_e32 v162, 1.0, v162
	v_add_f32_e32 v163, 1.0, v163
	v_add_f32_e32 v164, 1.0, v164
	v_add_f32_e32 v165, 1.0, v165
	v_rcp_f32_e32 v162, v162
	v_rcp_f32_e32 v163, v163
	v_rcp_f32_e32 v164, v164
	v_rcp_f32_e32 v165, v165
	v_mul_f32_e32 v162, v82, v162
	v_mul_f32_e32 v163, v83, v163
	v_mul_f32_e32 v164, v84, v164
	v_mul_f32_e32 v165, v85, v165
	v_mul_f32_e32 v162, v90, v162
	v_mul_f32_e32 v163, v91, v163
	v_mul_f32_e32 v164, v92, v164
	v_mul_f32_e32 v165, v93, v165
	v_cvt_pk_bf16_f32 v172, v162, v163
	v_cvt_pk_bf16_f32 v173, v164, v165
	v_mul_f32_e32 v162, 0xbfb8aa3b, v86
	v_mul_f32_e32 v163, 0xbfb8aa3b, v87
	v_mul_f32_e32 v164, 0xbfb8aa3b, v88
	v_mul_f32_e32 v165, 0xbfb8aa3b, v89
	v_exp_f32_e32 v162, v162
	v_exp_f32_e32 v163, v163
	v_exp_f32_e32 v164, v164
	v_exp_f32_e32 v165, v165
	v_add_f32_e32 v162, 1.0, v162
	v_add_f32_e32 v163, 1.0, v163
	v_add_f32_e32 v164, 1.0, v164
	v_add_f32_e32 v165, 1.0, v165
	v_rcp_f32_e32 v162, v162
	v_rcp_f32_e32 v163, v163
	v_rcp_f32_e32 v164, v164
	v_rcp_f32_e32 v165, v165
	v_mul_f32_e32 v162, v86, v162
	v_mul_f32_e32 v163, v87, v163
	v_mul_f32_e32 v164, v88, v164
	v_mul_f32_e32 v165, v89, v165
	v_mul_f32_e32 v162, v94, v162
	v_mul_f32_e32 v163, v95, v163
	v_mul_f32_e32 v164, v96, v164
	v_mul_f32_e32 v165, v97, v165
	v_cvt_pk_bf16_f32 v174, v162, v163
	v_cvt_pk_bf16_f32 v175, v164, v165
	s_nop 1
	v_permlane16_swap_b32_e32 v172, v174
	v_permlane16_swap_b32_e32 v173, v175
	global_store_dwordx4 v176, v[172:175], s[4:5] offset:128 sc1
	v_add_u32_e32 v176, 0x16000, v176
	v_mul_f32_e32 v162, 0xbfb8aa3b, v34
	v_mul_f32_e32 v163, 0xbfb8aa3b, v35
	v_mul_f32_e32 v164, 0xbfb8aa3b, v36
	v_mul_f32_e32 v165, 0xbfb8aa3b, v37
	v_exp_f32_e32 v162, v162
	v_exp_f32_e32 v163, v163
	v_exp_f32_e32 v164, v164
	v_exp_f32_e32 v165, v165
	v_add_f32_e32 v162, 1.0, v162
	v_add_f32_e32 v163, 1.0, v163
	v_add_f32_e32 v164, 1.0, v164
	v_add_f32_e32 v165, 1.0, v165
	v_rcp_f32_e32 v162, v162
	v_rcp_f32_e32 v163, v163
	v_rcp_f32_e32 v164, v164
	v_rcp_f32_e32 v165, v165
	v_mul_f32_e32 v162, v34, v162
	v_mul_f32_e32 v163, v35, v163
	v_mul_f32_e32 v164, v36, v164
	v_mul_f32_e32 v165, v37, v165
	v_mul_f32_e32 v162, v42, v162
	v_mul_f32_e32 v163, v43, v163
	v_mul_f32_e32 v164, v44, v164
	v_mul_f32_e32 v165, v45, v165
	v_cvt_pk_bf16_f32 v168, v162, v163
	v_cvt_pk_bf16_f32 v169, v164, v165
	v_mul_f32_e32 v162, 0xbfb8aa3b, v38
	v_mul_f32_e32 v163, 0xbfb8aa3b, v39
	v_mul_f32_e32 v164, 0xbfb8aa3b, v40
	v_mul_f32_e32 v165, 0xbfb8aa3b, v41
	v_exp_f32_e32 v162, v162
	v_exp_f32_e32 v163, v163
	v_exp_f32_e32 v164, v164
	v_exp_f32_e32 v165, v165
	v_add_f32_e32 v162, 1.0, v162
	v_add_f32_e32 v163, 1.0, v163
	v_add_f32_e32 v164, 1.0, v164
	v_add_f32_e32 v165, 1.0, v165
	v_rcp_f32_e32 v162, v162
	v_rcp_f32_e32 v163, v163
	v_rcp_f32_e32 v164, v164
	v_rcp_f32_e32 v165, v165
	v_mul_f32_e32 v162, v38, v162
	v_mul_f32_e32 v163, v39, v163
	v_mul_f32_e32 v164, v40, v164
	v_mul_f32_e32 v165, v41, v165
	v_mul_f32_e32 v162, v46, v162
	v_mul_f32_e32 v163, v47, v163
	v_mul_f32_e32 v164, v48, v164
	v_mul_f32_e32 v165, v49, v165
	v_cvt_pk_bf16_f32 v170, v162, v163
	v_cvt_pk_bf16_f32 v171, v164, v165
	s_nop 1
	v_permlane16_swap_b32_e32 v168, v170
	v_permlane16_swap_b32_e32 v169, v171
	global_store_dwordx4 v176, v[168:171], s[4:5] offset:0 sc1
	v_mul_f32_e32 v162, 0xbfb8aa3b, v98
	v_mul_f32_e32 v163, 0xbfb8aa3b, v99
	v_mul_f32_e32 v164, 0xbfb8aa3b, v100
	v_mul_f32_e32 v165, 0xbfb8aa3b, v101
	v_exp_f32_e32 v162, v162
	v_exp_f32_e32 v163, v163
	v_exp_f32_e32 v164, v164
	v_exp_f32_e32 v165, v165
	v_add_f32_e32 v162, 1.0, v162
	v_add_f32_e32 v163, 1.0, v163
	v_add_f32_e32 v164, 1.0, v164
	v_add_f32_e32 v165, 1.0, v165
	v_rcp_f32_e32 v162, v162
	v_rcp_f32_e32 v163, v163
	v_rcp_f32_e32 v164, v164
	v_rcp_f32_e32 v165, v165
	v_mul_f32_e32 v162, v98, v162
	v_mul_f32_e32 v163, v99, v163
	v_mul_f32_e32 v164, v100, v164
	v_mul_f32_e32 v165, v101, v165
	v_mul_f32_e32 v162, v106, v162
	v_mul_f32_e32 v163, v107, v163
	v_mul_f32_e32 v164, v108, v164
	v_mul_f32_e32 v165, v109, v165
	v_cvt_pk_bf16_f32 v172, v162, v163
	v_cvt_pk_bf16_f32 v173, v164, v165
	v_mul_f32_e32 v162, 0xbfb8aa3b, v102
	v_mul_f32_e32 v163, 0xbfb8aa3b, v103
	v_mul_f32_e32 v164, 0xbfb8aa3b, v104
	v_mul_f32_e32 v165, 0xbfb8aa3b, v105
	v_exp_f32_e32 v162, v162
	v_exp_f32_e32 v163, v163
	v_exp_f32_e32 v164, v164
	v_exp_f32_e32 v165, v165
	v_add_f32_e32 v162, 1.0, v162
	v_add_f32_e32 v163, 1.0, v163
	v_add_f32_e32 v164, 1.0, v164
	v_add_f32_e32 v165, 1.0, v165
	v_rcp_f32_e32 v162, v162
	v_rcp_f32_e32 v163, v163
	v_rcp_f32_e32 v164, v164
	v_rcp_f32_e32 v165, v165
	v_mul_f32_e32 v162, v102, v162
	v_mul_f32_e32 v163, v103, v163
	v_mul_f32_e32 v164, v104, v164
	v_mul_f32_e32 v165, v105, v165
	v_mul_f32_e32 v162, v110, v162
	v_mul_f32_e32 v163, v111, v163
	v_mul_f32_e32 v164, v112, v164
	v_mul_f32_e32 v165, v113, v165
	v_cvt_pk_bf16_f32 v174, v162, v163
	v_cvt_pk_bf16_f32 v175, v164, v165
	s_nop 1
	v_permlane16_swap_b32_e32 v172, v174
	v_permlane16_swap_b32_e32 v173, v175
	global_store_dwordx4 v176, v[172:175], s[4:5] offset:128 sc1
	v_add_u32_e32 v176, 0x16000, v176
	v_mul_f32_e32 v162, 0xbfb8aa3b, v50
	v_mul_f32_e32 v163, 0xbfb8aa3b, v51
	v_mul_f32_e32 v164, 0xbfb8aa3b, v52
	v_mul_f32_e32 v165, 0xbfb8aa3b, v53
	v_exp_f32_e32 v162, v162
	v_exp_f32_e32 v163, v163
	v_exp_f32_e32 v164, v164
	v_exp_f32_e32 v165, v165
	v_add_f32_e32 v162, 1.0, v162
	v_add_f32_e32 v163, 1.0, v163
	v_add_f32_e32 v164, 1.0, v164
	v_add_f32_e32 v165, 1.0, v165
	v_rcp_f32_e32 v162, v162
	v_rcp_f32_e32 v163, v163
	v_rcp_f32_e32 v164, v164
	v_rcp_f32_e32 v165, v165
	v_mul_f32_e32 v162, v50, v162
	v_mul_f32_e32 v163, v51, v163
	v_mul_f32_e32 v164, v52, v164
	v_mul_f32_e32 v165, v53, v165
	v_mul_f32_e32 v162, v58, v162
	v_mul_f32_e32 v163, v59, v163
	v_mul_f32_e32 v164, v60, v164
	v_mul_f32_e32 v165, v61, v165
	v_cvt_pk_bf16_f32 v168, v162, v163
	v_cvt_pk_bf16_f32 v169, v164, v165
	v_mul_f32_e32 v162, 0xbfb8aa3b, v54
	v_mul_f32_e32 v163, 0xbfb8aa3b, v55
	v_mul_f32_e32 v164, 0xbfb8aa3b, v56
	v_mul_f32_e32 v165, 0xbfb8aa3b, v57
	v_exp_f32_e32 v162, v162
	v_exp_f32_e32 v163, v163
	v_exp_f32_e32 v164, v164
	v_exp_f32_e32 v165, v165
	v_add_f32_e32 v162, 1.0, v162
	v_add_f32_e32 v163, 1.0, v163
	v_add_f32_e32 v164, 1.0, v164
	v_add_f32_e32 v165, 1.0, v165
	v_rcp_f32_e32 v162, v162
	v_rcp_f32_e32 v163, v163
	v_rcp_f32_e32 v164, v164
	v_rcp_f32_e32 v165, v165
	v_mul_f32_e32 v162, v54, v162
	v_mul_f32_e32 v163, v55, v163
	v_mul_f32_e32 v164, v56, v164
	v_mul_f32_e32 v165, v57, v165
	v_mul_f32_e32 v162, v62, v162
	v_mul_f32_e32 v163, v63, v163
	v_mul_f32_e32 v164, v64, v164
	v_mul_f32_e32 v165, v65, v165
	v_cvt_pk_bf16_f32 v170, v162, v163
	v_cvt_pk_bf16_f32 v171, v164, v165
	s_nop 1
	v_permlane16_swap_b32_e32 v168, v170
	v_permlane16_swap_b32_e32 v169, v171
	global_store_dwordx4 v176, v[168:171], s[4:5] offset:0 sc1
	v_mul_f32_e32 v162, 0xbfb8aa3b, v114
	v_mul_f32_e32 v163, 0xbfb8aa3b, v115
	v_mul_f32_e32 v164, 0xbfb8aa3b, v116
	v_mul_f32_e32 v165, 0xbfb8aa3b, v117
	v_exp_f32_e32 v162, v162
	v_exp_f32_e32 v163, v163
	v_exp_f32_e32 v164, v164
	v_exp_f32_e32 v165, v165
	v_add_f32_e32 v162, 1.0, v162
	v_add_f32_e32 v163, 1.0, v163
	v_add_f32_e32 v164, 1.0, v164
	v_add_f32_e32 v165, 1.0, v165
	v_rcp_f32_e32 v162, v162
	v_rcp_f32_e32 v163, v163
	v_rcp_f32_e32 v164, v164
	v_rcp_f32_e32 v165, v165
	v_mul_f32_e32 v162, v114, v162
	v_mul_f32_e32 v163, v115, v163
	v_mul_f32_e32 v164, v116, v164
	v_mul_f32_e32 v165, v117, v165
	v_mul_f32_e32 v162, v122, v162
	v_mul_f32_e32 v163, v123, v163
	v_mul_f32_e32 v164, v124, v164
	v_mul_f32_e32 v165, v125, v165
	v_cvt_pk_bf16_f32 v172, v162, v163
	v_cvt_pk_bf16_f32 v173, v164, v165
	v_mul_f32_e32 v162, 0xbfb8aa3b, v118
	v_mul_f32_e32 v163, 0xbfb8aa3b, v119
	v_mul_f32_e32 v164, 0xbfb8aa3b, v120
	v_mul_f32_e32 v165, 0xbfb8aa3b, v121
	v_exp_f32_e32 v162, v162
	v_exp_f32_e32 v163, v163
	v_exp_f32_e32 v164, v164
	v_exp_f32_e32 v165, v165
	v_add_f32_e32 v162, 1.0, v162
	v_add_f32_e32 v163, 1.0, v163
	v_add_f32_e32 v164, 1.0, v164
	v_add_f32_e32 v165, 1.0, v165
	v_rcp_f32_e32 v162, v162
	v_rcp_f32_e32 v163, v163
	v_rcp_f32_e32 v164, v164
	v_rcp_f32_e32 v165, v165
	v_mul_f32_e32 v162, v118, v162
	v_mul_f32_e32 v163, v119, v163
	v_mul_f32_e32 v164, v120, v164
	v_mul_f32_e32 v165, v121, v165
	v_mul_f32_e32 v162, v126, v162
	v_mul_f32_e32 v163, v127, v163
	v_mul_f32_e32 v164, v128, v164
	v_mul_f32_e32 v165, v129, v165
	v_cvt_pk_bf16_f32 v174, v162, v163
	v_cvt_pk_bf16_f32 v175, v164, v165
	s_nop 1
	v_permlane16_swap_b32_e32 v172, v174
	v_permlane16_swap_b32_e32 v173, v175
	global_store_dwordx4 v176, v[172:175], s[4:5] offset:128 sc1
	s_add_u32 s10, s10, 32
	s_cmp_lt_u32 s10, 64
	s_cbranch_scc1 .Lg2_a_item1
	s_cmp_lt_u32 s15, 8
	s_cbranch_scc0 .Lg2_a_noleft5
	s_lshr_b32 s12, s15, 2
	s_add_u32 s12, s12, 4
	s_mov_b32 s11, 10
	s_and_b32 s16, s15, 3
	s_lshl_b32 s16, s16, 6
	s_and_b32 s17, s14, 3
	s_mul_i32 s17, s17, 6
	s_add_u32 s12, s12, s17
	s_lshl_b32 s12, s12, 8
	s_add_u32 s12, s12, s16
	s_lshr_b32 s17, s14, 2
	s_mul_i32 s17, s17, 22
	s_lshl_b32 s11, s11, 1
	s_add_u32 s11, s11, s17
	s_lshl_b32 s16, s12, 11
	s_add_u32 s0, s24, s16
	s_addc_u32 s1, s25, 0
	s_lshl_b32 s16, s11, 18
	s_add_u32 s2, s40, s16
	s_addc_u32 s3, s41, 0
	s_mul_i32 s16, s12, 0x1600
	s_lshl_b32 s17, s11, 7
	s_add_u32 s16, s16, s17
	s_add_u32 s4, s26, s16
	s_addc_u32 s5, s27, 0
	v_lshrrev_b32_e32 v141, 8, v142
	v_lshlrev_b32_e32 v141, 17, v141
	v_sub_u32_e32 v141, v136, v141
	s_and_b32 s17, s6, 0xfff
	s_add_u32 m0, s17, 0x0
	s_nop 0
	global_load_lds_dwordx4 v141, s[0:1]
	s_add_u32 m0, s6, 0x4000
	s_nop 0
	global_load_lds_dwordx4 v136, s[2:3]
	s_add_u32 m0, s6, 0x6000
	s_nop 0
	global_load_lds_dwordx4 v137, s[2:3]
	s_add_u32 s0, s0, 1024
	s_addc_u32 s1, s1, 0
	s_add_u32 s2, s2, 1024
	s_addc_u32 s3, s3, 0
	s_add_u32 m0, s17, 0x8000
	s_nop 0
	global_load_lds_dwordx4 v141, s[0:1]
	s_add_u32 m0, s6, 0xc000
	s_nop 0
	global_load_lds_dwordx4 v136, s[2:3]
	s_add_u32 m0, s6, 0xe000
	s_nop 0
	global_load_lds_dwordx4 v137, s[2:3]
	s_add_u32 s0, s0, 1024
	s_addc_u32 s1, s1, 0
	s_add_u32 s2, s2, 1024
	s_addc_u32 s3, s3, 0
	s_add_u32 m0, s17, 0x10000
	s_nop 0
	global_load_lds_dwordx4 v141, s[0:1]
	s_add_u32 m0, s6, 0x14000
	s_nop 0
	global_load_lds_dwordx4 v136, s[2:3]
	s_add_u32 m0, s6, 0x16000
	s_nop 0
	global_load_lds_dwordx4 v137, s[2:3]
	s_add_u32 s0, s0, 1024
	s_addc_u32 s1, s1, 0
	s_add_u32 s2, s2, 1024
	s_addc_u32 s3, s3, 0
	v_lshrrev_b32_e32 v140, 7, v142
	v_lshlrev_b32_e32 v139, 12, v140
	v_sub_u32_e32 v134, v134, v139
	v_lshl_add_u32 v134, v140, 10, v134
	v_mul_u32_u24_e32 v139, 0x42000, v140
	v_sub_u32_e32 v138, v138, v139
	v_mov_b32_e32 v2, 0
	v_mov_b32_e32 v3, 0
	v_mov_b32_e32 v4, 0
	v_mov_b32_e32 v5, 0
	v_mov_b32_e32 v6, 0
	v_mov_b32_e32 v7, 0
	v_mov_b32_e32 v8, 0
	v_mov_b32_e32 v9, 0
	v_mov_b32_e32 v10, 0
	v_mov_b32_e32 v11, 0
	v_mov_b32_e32 v12, 0
	v_mov_b32_e32 v13, 0
	v_mov_b32_e32 v14, 0
	v_mov_b32_e32 v15, 0
	v_mov_b32_e32 v16, 0
	v_mov_b32_e32 v17, 0
	v_mov_b32_e32 v66, 0
	v_mov_b32_e32 v67, 0
	v_mov_b32_e32 v68, 0
	v_mov_b32_e32 v69, 0
	v_mov_b32_e32 v70, 0
	v_mov_b32_e32 v71, 0
	v_mov_b32_e32 v72, 0
	v_mov_b32_e32 v73, 0
	v_mov_b32_e32 v74, 0
	v_mov_b32_e32 v75, 0
	v_mov_b32_e32 v76, 0
	v_mov_b32_e32 v77, 0
	v_mov_b32_e32 v78, 0
	v_mov_b32_e32 v79, 0
	v_mov_b32_e32 v80, 0
	v_mov_b32_e32 v81, 0

.Lg2_a_klB8:
	s_waitcnt vmcnt(6)
	s_barrier
	v_add_u32_e32 v139, 0x0, v134
	v_add_u32_e32 v140, 0x0, v135
	ds_read_b128 v[162:165], v139 offset:0
	ds_read_b128 v[194:197], v140 offset:0
	ds_read_b128 v[198:201], v140 offset:1024
	ds_read_b128 v[202:205], v140 offset:2048
	ds_read_b128 v[206:209], v140 offset:3072
	v_mfma_f32_16x16x32_bf16 v[66:69], v[218:221], v[178:181], v[66:69]
	s_add_u32 m0, s17, 0x18000
	s_nop 0
	global_load_lds_dwordx4 v141, s[0:1]
	v_mfma_f32_16x16x32_bf16 v[70:73], v[222:225], v[178:181], v[70:73]
	v_mfma_f32_16x16x32_bf16 v[74:77], v[226:229], v[178:181], v[74:77]
	s_add_u32 m0, s6, 0x1c000
	s_nop 0
	global_load_lds_dwordx4 v136, s[2:3]
	v_mfma_f32_16x16x32_bf16 v[78:81], v[230:233], v[178:181], v[78:81]
	s_add_u32 m0, s6, 0x1e000
	s_nop 0
	global_load_lds_dwordx4 v137, s[2:3]
	s_add_u32 s0, s0, 1024
	s_addc_u32 s1, s1, 0
	s_add_u32 s2, s2, 1024
	s_addc_u32 s3, s3, 0
	ds_read_b128 v[218:221], v140 offset:8192
	ds_read_b128 v[222:225], v140 offset:9216
	ds_read_b128 v[226:229], v140 offset:10240
	ds_read_b128 v[230:233], v140 offset:11264
	s_waitcnt lgkmcnt(4)
	v_mfma_f32_16x16x32_bf16 v[2:5], v[194:197], v[162:165], v[2:5]
	v_mfma_f32_16x16x32_bf16 v[6:9], v[198:201], v[162:165], v[6:9]
	v_mfma_f32_16x16x32_bf16 v[10:13], v[202:205], v[162:165], v[10:13]
	v_mfma_f32_16x16x32_bf16 v[14:17], v[206:209], v[162:165], v[14:17]
	s_waitcnt lgkmcnt(0)
	s_waitcnt vmcnt(6)
	s_barrier
	v_add_u32_e32 v139, 0x8000, v134
	v_add_u32_e32 v140, 0x8000, v135
	ds_read_b128 v[178:181], v139 offset:0
	ds_read_b128 v[194:197], v140 offset:0
	ds_read_b128 v[198:201], v140 offset:1024
	ds_read_b128 v[202:205], v140 offset:2048
	ds_read_b128 v[206:209], v140 offset:3072
	v_mfma_f32_16x16x32_bf16 v[66:69], v[218:221], v[162:165], v[66:69]
	s_add_u32 m0, s17, 0x0
	s_nop 0
	global_load_lds_dwordx4 v141, s[0:1]
	v_mfma_f32_16x16x32_bf16 v[70:73], v[222:225], v[162:165], v[70:73]
	v_mfma_f32_16x16x32_bf16 v[74:77], v[226:229], v[162:165], v[74:77]
	s_add_u32 m0, s6, 0x4000
	s_nop 0
	global_load_lds_dwordx4 v136, s[2:3]
	v_mfma_f32_16x16x32_bf16 v[78:81], v[230:233], v[162:165], v[78:81]
	s_add_u32 m0, s6, 0x6000
	s_nop 0
	global_load_lds_dwordx4 v137, s[2:3]
	s_add_u32 s0, s0, 1024
	s_addc_u32 s1, s1, 0
	s_add_u32 s2, s2, 1024
	s_addc_u32 s3, s3, 0
	ds_read_b128 v[218:221], v140 offset:8192
	ds_read_b128 v[222:225], v140 offset:9216
	ds_read_b128 v[226:229], v140 offset:10240
	ds_read_b128 v[230:233], v140 offset:11264
	s_waitcnt lgkmcnt(4)
	v_mfma_f32_16x16x32_bf16 v[2:5], v[194:197], v[178:181], v[2:5]
	v_mfma_f32_16x16x32_bf16 v[6:9], v[198:201], v[178:181], v[6:9]
	v_mfma_f32_16x16x32_bf16 v[10:13], v[202:205], v[178:181], v[10:13]
	v_mfma_f32_16x16x32_bf16 v[14:17], v[206:209], v[178:181], v[14:17]
	s_waitcnt lgkmcnt(0)
	s_waitcnt vmcnt(6)
	s_barrier
	v_add_u32_e32 v139, 0x10000, v134
	v_add_u32_e32 v140, 0x10000, v135
	ds_read_b128 v[162:165], v139 offset:0
	ds_read_b128 v[194:197], v140 offset:0
	ds_read_b128 v[198:201], v140 offset:1024
	ds_read_b128 v[202:205], v140 offset:2048
	ds_read_b128 v[206:209], v140 offset:3072
	v_mfma_f32_16x16x32_bf16 v[66:69], v[218:221], v[178:181], v[66:69]
	s_add_u32 m0, s17, 0x8000
	s_nop 0
	global_load_lds_dwordx4 v141, s[0:1]
	v_mfma_f32_16x16x32_bf16 v[70:73], v[222:225], v[178:181], v[70:73]
	v_mfma_f32_16x16x32_bf16 v[74:77], v[226:229], v[178:181], v[74:77]
	s_add_u32 m0, s6, 0xc000
	s_nop 0
	global_load_lds_dwordx4 v136, s[2:3]
	v_mfma_f32_16x16x32_bf16 v[78:81], v[230:233], v[178:181], v[78:81]
	s_add_u32 m0, s6, 0xe000
	s_nop 0
	global_load_lds_dwordx4 v137, s[2:3]
	s_add_u32 s0, s0, 1024
	s_addc_u32 s1, s1, 0
	s_add_u32 s2, s2, 1024
	s_addc_u32 s3, s3, 0
	ds_read_b128 v[218:221], v140 offset:8192
	ds_read_b128 v[222:225], v140 offset:9216
	ds_read_b128 v[226:229], v140 offset:10240
	ds_read_b128 v[230:233], v140 offset:11264
	s_waitcnt lgkmcnt(4)
	v_mfma_f32_16x16x32_bf16 v[2:5], v[194:197], v[162:165], v[2:5]
	v_mfma_f32_16x16x32_bf16 v[6:9], v[198:201], v[162:165], v[6:9]
	v_mfma_f32_16x16x32_bf16 v[10:13], v[202:205], v[162:165], v[10:13]
	v_mfma_f32_16x16x32_bf16 v[14:17], v[206:209], v[162:165], v[14:17]
	s_waitcnt lgkmcnt(0)
	s_waitcnt vmcnt(6)
	s_barrier
	v_add_u32_e32 v139, 0x18000, v134
	v_add_u32_e32 v140, 0x18000, v135
	ds_read_b128 v[178:181], v139 offset:0
	ds_read_b128 v[194:197], v140 offset:0
	ds_read_b128 v[198:201], v140 offset:1024
	ds_read_b128 v[202:205], v140 offset:2048
	ds_read_b128 v[206:209], v140 offset:3072
	v_mfma_f32_16x16x32_bf16 v[66:69], v[218:221], v[162:165], v[66:69]
	s_add_u32 m0, s17, 0x10000
	s_nop 0
	global_load_lds_dwordx4 v141, s[0:1]
	v_mfma_f32_16x16x32_bf16 v[70:73], v[222:225], v[162:165], v[70:73]
	v_mfma_f32_16x16x32_bf16 v[74:77], v[226:229], v[162:165], v[74:77]
	s_add_u32 m0, s6, 0x14000
	s_nop 0
	global_load_lds_dwordx4 v136, s[2:3]
	v_mfma_f32_16x16x32_bf16 v[78:81], v[230:233], v[162:165], v[78:81]
	s_add_u32 m0, s6, 0x16000
	s_nop 0
	global_load_lds_dwordx4 v137, s[2:3]
	s_add_u32 s0, s0, 1024
	s_addc_u32 s1, s1, 0
	s_add_u32 s2, s2, 1024
	s_addc_u32 s3, s3, 0
	ds_read_b128 v[218:221], v140 offset:8192
	ds_read_b128 v[222:225], v140 offset:9216
	ds_read_b128 v[226:229], v140 offset:10240
	ds_read_b128 v[230:233], v140 offset:11264
	s_waitcnt lgkmcnt(4)
	v_mfma_f32_16x16x32_bf16 v[2:5], v[194:197], v[178:181], v[2:5]
	v_mfma_f32_16x16x32_bf16 v[6:9], v[198:201], v[178:181], v[6:9]
	v_mfma_f32_16x16x32_bf16 v[10:13], v[202:205], v[178:181], v[10:13]
	v_mfma_f32_16x16x32_bf16 v[14:17], v[206:209], v[178:181], v[14:17]
	s_waitcnt lgkmcnt(0)
	s_sub_u32 s7, s7, 1
	s_cmp_lg_u32 s7, 0
	s_cbranch_scc1 .Lg2_a_klB8
	s_waitcnt vmcnt(6)
	s_barrier
	v_add_u32_e32 v139, 0x0, v134
	v_add_u32_e32 v140, 0x0, v135
	ds_read_b128 v[162:165], v139 offset:0
	ds_read_b128 v[194:197], v140 offset:0
	ds_read_b128 v[198:201], v140 offset:1024
	ds_read_b128 v[202:205], v140 offset:2048
	ds_read_b128 v[206:209], v140 offset:3072
	v_mfma_f32_16x16x32_bf16 v[66:69], v[218:221], v[178:181], v[66:69]
	s_add_u32 m0, s17, 0x18000
	s_nop 0
	global_load_lds_dwordx4 v141, s[0:1]
	v_mfma_f32_16x16x32_bf16 v[70:73], v[222:225], v[178:181], v[70:73]
	v_mfma_f32_16x16x32_bf16 v[74:77], v[226:229], v[178:181], v[74:77]
	s_add_u32 m0, s6, 0x1c000
	s_nop 0
	global_load_lds_dwordx4 v136, s[2:3]
	v_mfma_f32_16x16x32_bf16 v[78:81], v[230:233], v[178:181], v[78:81]
	s_add_u32 m0, s6, 0x1e000
	s_nop 0
	global_load_lds_dwordx4 v137, s[2:3]
	s_add_u32 s0, s0, 1024
	s_addc_u32 s1, s1, 0
	s_add_u32 s2, s2, 1024
	s_addc_u32 s3, s3, 0
	ds_read_b128 v[218:221], v140 offset:8192
	ds_read_b128 v[222:225], v140 offset:9216
	ds_read_b128 v[226:229], v140 offset:10240
	ds_read_b128 v[230:233], v140 offset:11264
	s_waitcnt lgkmcnt(4)
	v_mfma_f32_16x16x32_bf16 v[2:5], v[194:197], v[162:165], v[2:5]
	v_mfma_f32_16x16x32_bf16 v[6:9], v[198:201], v[162:165], v[6:9]
	v_mfma_f32_16x16x32_bf16 v[10:13], v[202:205], v[162:165], v[10:13]
	v_mfma_f32_16x16x32_bf16 v[14:17], v[206:209], v[162:165], v[14:17]
	s_waitcnt lgkmcnt(0)
	s_waitcnt vmcnt(6)
	s_barrier
	v_add_u32_e32 v139, 0x8000, v134
	v_add_u32_e32 v140, 0x8000, v135
	ds_read_b128 v[178:181], v139 offset:0
	ds_read_b128 v[194:197], v140 offset:0
	ds_read_b128 v[198:201], v140 offset:1024
	ds_read_b128 v[202:205], v140 offset:2048
	ds_read_b128 v[206:209], v140 offset:3072
	v_mfma_f32_16x16x32_bf16 v[66:69], v[218:221], v[162:165], v[66:69]
	v_mfma_f32_16x16x32_bf16 v[70:73], v[222:225], v[162:165], v[70:73]
	v_mfma_f32_16x16x32_bf16 v[74:77], v[226:229], v[162:165], v[74:77]
	v_mfma_f32_16x16x32_bf16 v[78:81], v[230:233], v[162:165], v[78:81]
	ds_read_b128 v[218:221], v140 offset:8192
	ds_read_b128 v[222:225], v140 offset:9216
	ds_read_b128 v[226:229], v140 offset:10240
	ds_read_b128 v[230:233], v140 offset:11264
	s_waitcnt lgkmcnt(4)
	v_mfma_f32_16x16x32_bf16 v[2:5], v[194:197], v[178:181], v[2:5]
	v_mfma_f32_16x16x32_bf16 v[6:9], v[198:201], v[178:181], v[6:9]
	v_mfma_f32_16x16x32_bf16 v[10:13], v[202:205], v[178:181], v[10:13]
	v_mfma_f32_16x16x32_bf16 v[14:17], v[206:209], v[178:181], v[14:17]
	s_waitcnt lgkmcnt(0)
	s_waitcnt vmcnt(3)
	s_barrier
	v_add_u32_e32 v139, 0x10000, v134
	v_add_u32_e32 v140, 0x10000, v135
	ds_read_b128 v[162:165], v139 offset:0
	ds_read_b128 v[194:197], v140 offset:0
	ds_read_b128 v[198:201], v140 offset:1024
	ds_read_b128 v[202:205], v140 offset:2048
	ds_read_b128 v[206:209], v140 offset:3072
	v_mfma_f32_16x16x32_bf16 v[66:69], v[218:221], v[178:181], v[66:69]
	v_mfma_f32_16x16x32_bf16 v[70:73], v[222:225], v[178:181], v[70:73]
	v_mfma_f32_16x16x32_bf16 v[74:77], v[226:229], v[178:181], v[74:77]
	v_mfma_f32_16x16x32_bf16 v[78:81], v[230:233], v[178:181], v[78:81]
	ds_read_b128 v[218:221], v140 offset:8192
	ds_read_b128 v[222:225], v140 offset:9216
	ds_read_b128 v[226:229], v140 offset:10240
	ds_read_b128 v[230:233], v140 offset:11264
	s_waitcnt lgkmcnt(4)
	v_mfma_f32_16x16x32_bf16 v[2:5], v[194:197], v[162:165], v[2:5]
	v_mfma_f32_16x16x32_bf16 v[6:9], v[198:201], v[162:165], v[6:9]
	v_mfma_f32_16x16x32_bf16 v[10:13], v[202:205], v[162:165], v[10:13]
	v_mfma_f32_16x16x32_bf16 v[14:17], v[206:209], v[162:165], v[14:17]
	s_waitcnt lgkmcnt(0)
	s_waitcnt vmcnt(0)
	s_barrier
	v_add_u32_e32 v139, 0x18000, v134
	v_add_u32_e32 v140, 0x18000, v135
	ds_read_b128 v[178:181], v139 offset:0
	ds_read_b128 v[194:197], v140 offset:0
	ds_read_b128 v[198:201], v140 offset:1024
	ds_read_b128 v[202:205], v140 offset:2048
	ds_read_b128 v[206:209], v140 offset:3072
	v_mfma_f32_16x16x32_bf16 v[66:69], v[218:221], v[162:165], v[66:69]
	v_mfma_f32_16x16x32_bf16 v[70:73], v[222:225], v[162:165], v[70:73]
	v_mfma_f32_16x16x32_bf16 v[74:77], v[226:229], v[162:165], v[74:77]
	v_mfma_f32_16x16x32_bf16 v[78:81], v[230:233], v[162:165], v[78:81]
	ds_read_b128 v[218:221], v140 offset:8192
	ds_read_b128 v[222:225], v140 offset:9216
	ds_read_b128 v[226:229], v140 offset:10240
	ds_read_b128 v[230:233], v140 offset:11264
	s_waitcnt lgkmcnt(4)
	v_mfma_f32_16x16x32_bf16 v[2:5], v[194:197], v[178:181], v[2:5]
	v_mfma_f32_16x16x32_bf16 v[6:9], v[198:201], v[178:181], v[6:9]
	v_mfma_f32_16x16x32_bf16 v[10:13], v[202:205], v[178:181], v[10:13]
	v_mfma_f32_16x16x32_bf16 v[14:17], v[206:209], v[178:181], v[14:17]
	s_waitcnt lgkmcnt(0)
	v_mfma_f32_16x16x32_bf16 v[66:69], v[218:221], v[178:181], v[66:69]
	v_mfma_f32_16x16x32_bf16 v[70:73], v[222:225], v[178:181], v[70:73]
	v_mfma_f32_16x16x32_bf16 v[74:77], v[226:229], v[178:181], v[74:77]
	v_mfma_f32_16x16x32_bf16 v[78:81], v[230:233], v[178:181], v[78:81]

.LBB0_72:
	v_readlane_b32 s4, v217, 0
	v_readlane_b32 s5, v214, 57
	v_readlane_b32 s38, v217, 1
	v_readlane_b32 s39, v217, 2
	v_lshrrev_b32_e32 v197, 6, v142
	s_sub_u32 s38, s38, 0xd0
	s_subb_u32 s39, s39, 0
	v_readfirstlane_b32 s6, v197
	s_load_dwordx2 s[38:39], s[38:39], 0x40
	v_and_b32_e32 v194, 63, v142
	v_and_b32_e32 v195, 7, v194
	v_lshlrev_b32_e32 v195, 3, v195
	v_lshrrev_b32_e32 v197, 3, v194
	v_lshl_add_u32 v195, v197, 10, v195
	v_lshlrev_b32_e32 v194, 4, v194
	v_mov_b32_e32 v196, 0x358637bd
	s_lshr_b32 s7, s4, 3
	s_lshl_b32 s7, s7, 3
	s_add_u32 s7, s7, s6
	s_and_b32 s10, s4, 7
	s_mul_i32 s10, s10, 192
	s_add_u32 s11, s7, 0
	s_mul_i32 s12, s11, 43691
	s_lshr_b32 s12, s12, 23
	s_mul_i32 s12, s12, 1344
	s_add_u32 s11, s11, s12
	s_add_u32 s98, s11, s10
	s_add_u32 s11, s7, 256
	s_mul_i32 s12, s11, 43691
	s_lshr_b32 s12, s12, 23
	s_mul_i32 s12, s12, 1344
	s_add_u32 s11, s11, s12
	s_add_u32 s99, s11, s10
	s_add_u32 s11, s7, 512
	s_mul_i32 s12, s11, 43691
	s_lshr_b32 s12, s12, 23
	s_mul_i32 s12, s12, 1344
	s_add_u32 s11, s11, s12
	s_add_u32 s17, s11, s10
	s_waitcnt lgkmcnt(0)
	s_lshl_b32 s11, s98, 12
	s_add_u32 s68, s48, s11
	s_addc_u32 s69, s49, 0
	global_load_dwordx4 v[2:5], v194, s[68:69] offset:0
	global_load_dwordx4 v[6:9], v194, s[68:69] offset:1024
	global_load_dwordx4 v[10:13], v194, s[68:69] offset:2048
	global_load_dwordx4 v[14:17], v194, s[68:69] offset:3072
	s_lshl_b32 s11, s99, 12
	s_add_u32 s70, s48, s11
	s_addc_u32 s71, s49, 0
	global_load_dwordx4 v[18:21], v194, s[70:71] offset:0
	global_load_dwordx4 v[22:25], v194, s[70:71] offset:1024
	global_load_dwordx4 v[26:29], v194, s[70:71] offset:2048
	global_load_dwordx4 v[30:33], v194, s[70:71] offset:3072
	s_lshl_b32 s11, s17, 12
	s_add_u32 s72, s48, s11
	s_addc_u32 s73, s49, 0
	global_load_dwordx4 v[34:37], v194, s[72:73] offset:0
	global_load_dwordx4 v[38:41], v194, s[72:73] offset:1024
	global_load_dwordx4 v[42:45], v194, s[72:73] offset:2048
	global_load_dwordx4 v[46:49], v194, s[72:73] offset:3072
	s_mov_b32 s42, s17
	s_mul_i32 s11, s5, 3
	s_add_u32 s11, s11, 2
	s_lshl_b32 s11, s11, 12
	s_add_u32 s38, s38, s11
	s_addc_u32 s39, s39, 0
	global_load_dwordx4 v[50:53], v194, s[38:39] offset:0
	global_load_dwordx4 v[54:57], v194, s[38:39] offset:1024
	global_load_dwordx4 v[58:61], v194, s[38:39] offset:2048
	global_load_dwordx4 v[62:65], v194, s[38:39] offset:3072
	s_sub_u32 s11, s98, 0x1000
	s_lshr_b32 s11, s11, 10
	s_add_u32 s11, s11, 1
	s_cmp_lt_u32 s98, 0x1000
	s_cselect_b32 s11, 0, s11
	s_mul_i32 s12, s5, 3
	s_add_u32 s11, s11, s12
	s_mul_i32 s11, s11, 0x9000
	s_add_u32 s11, s11, 0x6000
	s_add_u32 s74, s34, s11
	s_addc_u32 s75, s35, 0
	s_add_u32 s80, s74, 0x1000
	s_addc_u32 s81, s75, 0
	global_load_dwordx4 v[66:69], v194, s[74:75] offset:0
	global_load_dwordx4 v[70:73], v194, s[74:75] offset:1024
	global_load_dwordx4 v[74:77], v194, s[74:75] offset:2048
	global_load_dwordx4 v[78:81], v194, s[74:75] offset:3072
	global_load_dwordx4 v[114:117], v194, s[80:81] offset:0
	global_load_dwordx4 v[118:121], v194, s[80:81] offset:1024
	global_load_dwordx4 v[122:125], v194, s[80:81] offset:2048
	global_load_dwordx4 v[126:129], v194, s[80:81] offset:3072
	s_sub_u32 s11, s99, 0x1000
	s_lshr_b32 s11, s11, 10
	s_add_u32 s11, s11, 1
	s_cmp_lt_u32 s99, 0x1000
	s_cselect_b32 s11, 0, s11
	s_mul_i32 s12, s5, 3
	s_add_u32 s11, s11, s12
	s_mul_i32 s11, s11, 0x9000
	s_add_u32 s11, s11, 0x6000
	s_add_u32 s76, s34, s11
	s_addc_u32 s77, s35, 0
	s_add_u32 s82, s76, 0x1000
	s_addc_u32 s83, s77, 0
	global_load_dwordx4 v[82:85], v194, s[76:77] offset:0
	global_load_dwordx4 v[86:89], v194, s[76:77] offset:1024
	global_load_dwordx4 v[90:93], v194, s[76:77] offset:2048
	global_load_dwordx4 v[94:97], v194, s[76:77] offset:3072
	global_load_dwordx4 v[162:165], v194, s[82:83] offset:0
	global_load_dwordx4 v[166:169], v194, s[82:83] offset:1024
	global_load_dwordx4 v[170:173], v194, s[82:83] offset:2048
	global_load_dwordx4 v[174:177], v194, s[82:83] offset:3072
	s_sub_u32 s11, s42, 0x1000
	s_lshr_b32 s11, s11, 10
	s_add_u32 s11, s11, 1
	s_cmp_lt_u32 s42, 0x1000
	s_cselect_b32 s11, 0, s11
	s_mul_i32 s12, s5, 3
	s_add_u32 s11, s11, s12
	s_mul_i32 s11, s11, 0x9000
	s_add_u32 s11, s11, 0x6000
	s_add_u32 s78, s34, s11
	s_addc_u32 s79, s35, 0
	s_add_u32 s92, s78, 0x1000
	s_addc_u32 s93, s79, 0
	global_load_dwordx4 v[98:101], v194, s[78:79] offset:0
	global_load_dwordx4 v[102:105], v194, s[78:79] offset:1024
	global_load_dwordx4 v[106:109], v194, s[78:79] offset:2048
	global_load_dwordx4 v[110:113], v194, s[78:79] offset:3072
	global_load_dwordx4 v[178:181], v194, s[92:93] offset:0
	global_load_dwordx4 v[182:185], v194, s[92:93] offset:1024
	global_load_dwordx4 v[186:189], v194, s[92:93] offset:2048
	global_load_dwordx4 v[190:193], v194, s[92:93] offset:3072
	s_waitcnt vmcnt(28)
	s_lshr_b32 s11, s98, 4
	s_lshl_b32 s11, s11, 15
	s_and_b32 s12, s98, 15
	s_lshl_b32 s12, s12, 6
	s_add_u32 s11, s11, s12
	s_add_u32 s68, s24, s11
	s_addc_u32 s69, s25, 0
	s_lshr_b32 s11, s99, 4
	s_lshl_b32 s11, s11, 15
	s_and_b32 s12, s99, 15
	s_lshl_b32 s12, s12, 6
	s_add_u32 s11, s11, s12
	s_add_u32 s70, s24, s11
	s_addc_u32 s71, s25, 0
	s_lshr_b32 s11, s42, 4
	s_lshl_b32 s11, s11, 15
	s_and_b32 s12, s42, 15
	s_lshl_b32 s12, s12, 6
	s_add_u32 s11, s11, s12
	s_add_u32 s72, s24, s11
	s_addc_u32 s73, s25, 0
	v_mul_f32_e32 v198, v2, v2
	v_mul_f32_e32 v199, v18, v18
	v_mul_f32_e32 v200, v34, v34
	v_fmac_f32_e32 v198, v3, v3
	v_fmac_f32_e32 v199, v19, v19
	v_fmac_f32_e32 v200, v35, v35
	v_fmac_f32_e32 v198, v4, v4
	v_fmac_f32_e32 v199, v20, v20
	v_fmac_f32_e32 v200, v36, v36
	v_fmac_f32_e32 v198, v5, v5
	v_fmac_f32_e32 v199, v21, v21
	v_fmac_f32_e32 v200, v37, v37
	v_fmac_f32_e32 v198, v6, v6
	v_fmac_f32_e32 v199, v22, v22
	v_fmac_f32_e32 v200, v38, v38
	v_fmac_f32_e32 v198, v7, v7
	v_fmac_f32_e32 v199, v23, v23
	v_fmac_f32_e32 v200, v39, v39
	v_fmac_f32_e32 v198, v8, v8
	v_fmac_f32_e32 v199, v24, v24
	v_fmac_f32_e32 v200, v40, v40
	v_fmac_f32_e32 v198, v9, v9
	v_fmac_f32_e32 v199, v25, v25
	v_fmac_f32_e32 v200, v41, v41
	v_fmac_f32_e32 v198, v10, v10
	v_fmac_f32_e32 v199, v26, v26
	v_fmac_f32_e32 v200, v42, v42
	v_fmac_f32_e32 v198, v11, v11
	v_fmac_f32_e32 v199, v27, v27
	v_fmac_f32_e32 v200, v43, v43
	v_fmac_f32_e32 v198, v12, v12
	v_fmac_f32_e32 v199, v28, v28
	v_fmac_f32_e32 v200, v44, v44
	v_fmac_f32_e32 v198, v13, v13
	v_fmac_f32_e32 v199, v29, v29
	v_fmac_f32_e32 v200, v45, v45
	v_fmac_f32_e32 v198, v14, v14
	v_fmac_f32_e32 v199, v30, v30
	v_fmac_f32_e32 v200, v46, v46
	v_fmac_f32_e32 v198, v15, v15
	v_fmac_f32_e32 v199, v31, v31
	v_fmac_f32_e32 v200, v47, v47
	v_fmac_f32_e32 v198, v16, v16
	v_fmac_f32_e32 v199, v32, v32
	v_fmac_f32_e32 v200, v48, v48
	v_fmac_f32_e32 v198, v17, v17
	v_fmac_f32_e32 v199, v33, v33
	v_fmac_f32_e32 v200, v49, v49
	s_nop 1
	v_add_f32_dpp v198, v198, v198 quad_perm:[1,0,3,2] row_mask:0xf bank_mask:0xf
	v_add_f32_dpp v199, v199, v199 quad_perm:[1,0,3,2] row_mask:0xf bank_mask:0xf
	v_add_f32_dpp v200, v200, v200 quad_perm:[1,0,3,2] row_mask:0xf bank_mask:0xf
	s_nop 1
	v_add_f32_dpp v198, v198, v198 quad_perm:[2,3,0,1] row_mask:0xf bank_mask:0xf
	v_add_f32_dpp v199, v199, v199 quad_perm:[2,3,0,1] row_mask:0xf bank_mask:0xf
	v_add_f32_dpp v200, v200, v200 quad_perm:[2,3,0,1] row_mask:0xf bank_mask:0xf
	s_nop 1
	v_add_f32_dpp v198, v198, v198 row_half_mirror row_mask:0xf bank_mask:0xf
	v_add_f32_dpp v199, v199, v199 row_half_mirror row_mask:0xf bank_mask:0xf
	v_add_f32_dpp v200, v200, v200 row_half_mirror row_mask:0xf bank_mask:0xf
	s_nop 1
	v_add_f32_dpp v198, v198, v198 row_mirror row_mask:0xf bank_mask:0xf
	v_add_f32_dpp v199, v199, v199 row_mirror row_mask:0xf bank_mask:0xf
	v_add_f32_dpp v200, v200, v200 row_mirror row_mask:0xf bank_mask:0xf
	s_nop 1
	v_add_f32_dpp v198, v198, v198 row_bcast:15 row_mask:0xa bank_mask:0xf
	v_add_f32_dpp v199, v199, v199 row_bcast:15 row_mask:0xa bank_mask:0xf
	v_add_f32_dpp v200, v200, v200 row_bcast:15 row_mask:0xa bank_mask:0xf
	s_nop 1
	v_add_f32_dpp v198, v198, v198 row_bcast:31 row_mask:0xc bank_mask:0xf
	v_add_f32_dpp v199, v199, v199 row_bcast:31 row_mask:0xc bank_mask:0xf
	v_add_f32_dpp v200, v200, v200 row_bcast:31 row_mask:0xc bank_mask:0xf
	s_nop 1
	v_readlane_b32 s32, v198, 63
	v_readlane_b32 s20, v199, 63
	v_readlane_b32 s94, v200, 63
	s_nop 0
	v_mov_b32_e32 v201, s32
	v_mov_b32_e32 v202, s20
	v_mov_b32_e32 v203, s94
	v_fmamk_f32 v201, v201, 0x3a800000, v196
	v_fmamk_f32 v202, v202, 0x3a800000, v196
	v_fmamk_f32 v203, v203, 0x3a800000, v196
	v_rsq_f32_e32 v201, v201
	v_rsq_f32_e32 v202, v202
	v_rsq_f32_e32 v203, v203
	s_waitcnt vmcnt(0)
	v_mul_f32_e32 v204, v2, v201
	v_mul_f32_e32 v205, v3, v201
	v_mul_f32_e32 v206, v4, v201
	v_mul_f32_e32 v207, v5, v201
	v_mul_f32_e32 v204, v50, v204
	v_mul_f32_e32 v205, v51, v205
	v_mul_f32_e32 v206, v52, v206
	v_mul_f32_e32 v207, v53, v207
	v_add_f32_e32 v114, 1.0, v114
	v_add_f32_e32 v115, 1.0, v115
	v_add_f32_e32 v116, 1.0, v116
	v_add_f32_e32 v117, 1.0, v117
	v_fma_f32 v204, v114, v204, v66
	v_fma_f32 v205, v115, v205, v67
	v_fma_f32 v206, v116, v206, v68
	v_fma_f32 v207, v117, v207, v69
	v_cvt_pk_bf16_f32 v208, v204, v205
	v_cvt_pk_bf16_f32 v209, v206, v207
	s_add_u32 s14, s68, 0x0
	s_addc_u32 s15, s69, 0
	global_store_dwordx2 v195, v[208:209], s[14:15]
	v_mul_f32_e32 v204, v6, v201
	v_mul_f32_e32 v205, v7, v201
	v_mul_f32_e32 v206, v8, v201
	v_mul_f32_e32 v207, v9, v201
	v_mul_f32_e32 v204, v54, v204
	v_mul_f32_e32 v205, v55, v205
	v_mul_f32_e32 v206, v56, v206
	v_mul_f32_e32 v207, v57, v207
	v_add_f32_e32 v118, 1.0, v118
	v_add_f32_e32 v119, 1.0, v119
	v_add_f32_e32 v120, 1.0, v120
	v_add_f32_e32 v121, 1.0, v121
	v_fma_f32 v204, v118, v204, v70
	v_fma_f32 v205, v119, v205, v71
	v_fma_f32 v206, v120, v206, v72
	v_fma_f32 v207, v121, v207, v73
	v_cvt_pk_bf16_f32 v210, v204, v205
	v_cvt_pk_bf16_f32 v211, v206, v207
	s_add_u32 s14, s68, 0x2000
	s_addc_u32 s15, s69, 0
	global_store_dwordx2 v195, v[210:211], s[14:15]
	v_mul_f32_e32 v204, v10, v201
	v_mul_f32_e32 v205, v11, v201
	v_mul_f32_e32 v206, v12, v201
	v_mul_f32_e32 v207, v13, v201
	v_mul_f32_e32 v204, v58, v204
	v_mul_f32_e32 v205, v59, v205
	v_mul_f32_e32 v206, v60, v206
	v_mul_f32_e32 v207, v61, v207
	v_add_f32_e32 v122, 1.0, v122
	v_add_f32_e32 v123, 1.0, v123
	v_add_f32_e32 v124, 1.0, v124
	v_add_f32_e32 v125, 1.0, v125
	v_fma_f32 v204, v122, v204, v74
	v_fma_f32 v205, v123, v205, v75
	v_fma_f32 v206, v124, v206, v76
	v_fma_f32 v207, v125, v207, v77
	v_cvt_pk_bf16_f32 v208, v204, v205
	v_cvt_pk_bf16_f32 v209, v206, v207
	s_add_u32 s14, s68, 0x4000
	s_addc_u32 s15, s69, 0
	global_store_dwordx2 v195, v[208:209], s[14:15]
	v_mul_f32_e32 v204, v14, v201
	v_mul_f32_e32 v205, v15, v201
	v_mul_f32_e32 v206, v16, v201
	v_mul_f32_e32 v207, v17, v201
	v_mul_f32_e32 v204, v62, v204
	v_mul_f32_e32 v205, v63, v205
	v_mul_f32_e32 v206, v64, v206
	v_mul_f32_e32 v207, v65, v207
	v_add_f32_e32 v126, 1.0, v126
	v_add_f32_e32 v127, 1.0, v127
	v_add_f32_e32 v128, 1.0, v128
	v_add_f32_e32 v129, 1.0, v129
	v_fma_f32 v204, v126, v204, v78
	v_fma_f32 v205, v127, v205, v79
	v_fma_f32 v206, v128, v206, v80
	v_fma_f32 v207, v129, v207, v81
	v_cvt_pk_bf16_f32 v210, v204, v205
	v_cvt_pk_bf16_f32 v211, v206, v207
	s_add_u32 s14, s68, 0x6000
	s_addc_u32 s15, s69, 0
	global_store_dwordx2 v195, v[210:211], s[14:15]
	v_mul_f32_e32 v204, v18, v202
	v_mul_f32_e32 v205, v19, v202
	v_mul_f32_e32 v206, v20, v202
	v_mul_f32_e32 v207, v21, v202
	v_mul_f32_e32 v204, v50, v204
	v_mul_f32_e32 v205, v51, v205
	v_mul_f32_e32 v206, v52, v206
	v_mul_f32_e32 v207, v53, v207
	v_add_f32_e32 v162, 1.0, v162
	v_add_f32_e32 v163, 1.0, v163
	v_add_f32_e32 v164, 1.0, v164
	v_add_f32_e32 v165, 1.0, v165
	v_fma_f32 v204, v162, v204, v82
	v_fma_f32 v205, v163, v205, v83
	v_fma_f32 v206, v164, v206, v84
	v_fma_f32 v207, v165, v207, v85
	v_cvt_pk_bf16_f32 v208, v204, v205
	v_cvt_pk_bf16_f32 v209, v206, v207
	s_add_u32 s14, s70, 0x0
	s_addc_u32 s15, s71, 0
	global_store_dwordx2 v195, v[208:209], s[14:15]
	v_mul_f32_e32 v204, v22, v202
	v_mul_f32_e32 v205, v23, v202
	v_mul_f32_e32 v206, v24, v202
	v_mul_f32_e32 v207, v25, v202
	v_mul_f32_e32 v204, v54, v204
	v_mul_f32_e32 v205, v55, v205
	v_mul_f32_e32 v206, v56, v206
	v_mul_f32_e32 v207, v57, v207
	v_add_f32_e32 v166, 1.0, v166
	v_add_f32_e32 v167, 1.0, v167
	v_add_f32_e32 v168, 1.0, v168
	v_add_f32_e32 v169, 1.0, v169
	v_fma_f32 v204, v166, v204, v86
	v_fma_f32 v205, v167, v205, v87
	v_fma_f32 v206, v168, v206, v88
	v_fma_f32 v207, v169, v207, v89
	v_cvt_pk_bf16_f32 v210, v204, v205
	v_cvt_pk_bf16_f32 v211, v206, v207
	s_add_u32 s14, s70, 0x2000
	s_addc_u32 s15, s71, 0
	global_store_dwordx2 v195, v[210:211], s[14:15]
	v_mul_f32_e32 v204, v26, v202
	v_mul_f32_e32 v205, v27, v202
	v_mul_f32_e32 v206, v28, v202
	v_mul_f32_e32 v207, v29, v202
	v_mul_f32_e32 v204, v58, v204
	v_mul_f32_e32 v205, v59, v205
	v_mul_f32_e32 v206, v60, v206
	v_mul_f32_e32 v207, v61, v207
	v_add_f32_e32 v170, 1.0, v170
	v_add_f32_e32 v171, 1.0, v171
	v_add_f32_e32 v172, 1.0, v172
	v_add_f32_e32 v173, 1.0, v173
	v_fma_f32 v204, v170, v204, v90
	v_fma_f32 v205, v171, v205, v91
	v_fma_f32 v206, v172, v206, v92
	v_fma_f32 v207, v173, v207, v93
	v_cvt_pk_bf16_f32 v208, v204, v205
	v_cvt_pk_bf16_f32 v209, v206, v207
	s_add_u32 s14, s70, 0x4000
	s_addc_u32 s15, s71, 0
	global_store_dwordx2 v195, v[208:209], s[14:15]
	v_mul_f32_e32 v204, v30, v202
	v_mul_f32_e32 v205, v31, v202
	v_mul_f32_e32 v206, v32, v202
	v_mul_f32_e32 v207, v33, v202
	v_mul_f32_e32 v204, v62, v204
	v_mul_f32_e32 v205, v63, v205
	v_mul_f32_e32 v206, v64, v206
	v_mul_f32_e32 v207, v65, v207
	v_add_f32_e32 v174, 1.0, v174
	v_add_f32_e32 v175, 1.0, v175
	v_add_f32_e32 v176, 1.0, v176
	v_add_f32_e32 v177, 1.0, v177
	v_fma_f32 v204, v174, v204, v94
	v_fma_f32 v205, v175, v205, v95
	v_fma_f32 v206, v176, v206, v96
	v_fma_f32 v207, v177, v207, v97
	v_cvt_pk_bf16_f32 v210, v204, v205
	v_cvt_pk_bf16_f32 v211, v206, v207
	s_add_u32 s14, s70, 0x6000
	s_addc_u32 s15, s71, 0
	global_store_dwordx2 v195, v[210:211], s[14:15]
	v_mul_f32_e32 v204, v34, v203
	v_mul_f32_e32 v205, v35, v203
	v_mul_f32_e32 v206, v36, v203
	v_mul_f32_e32 v207, v37, v203
	v_mul_f32_e32 v204, v50, v204
	v_mul_f32_e32 v205, v51, v205
	v_mul_f32_e32 v206, v52, v206
	v_mul_f32_e32 v207, v53, v207
	v_add_f32_e32 v178, 1.0, v178
	v_add_f32_e32 v179, 1.0, v179
	v_add_f32_e32 v180, 1.0, v180
	v_add_f32_e32 v181, 1.0, v181
	v_fma_f32 v204, v178, v204, v98
	v_fma_f32 v205, v179, v205, v99
	v_fma_f32 v206, v180, v206, v100
	v_fma_f32 v207, v181, v207, v101
	v_cvt_pk_bf16_f32 v208, v204, v205
	v_cvt_pk_bf16_f32 v209, v206, v207
	s_add_u32 s14, s72, 0x0
	s_addc_u32 s15, s73, 0
	global_store_dwordx2 v195, v[208:209], s[14:15]
	v_mul_f32_e32 v204, v38, v203
	v_mul_f32_e32 v205, v39, v203
	v_mul_f32_e32 v206, v40, v203
	v_mul_f32_e32 v207, v41, v203
	v_mul_f32_e32 v204, v54, v204
	v_mul_f32_e32 v205, v55, v205
	v_mul_f32_e32 v206, v56, v206
	v_mul_f32_e32 v207, v57, v207
	v_add_f32_e32 v182, 1.0, v182
	v_add_f32_e32 v183, 1.0, v183
	v_add_f32_e32 v184, 1.0, v184
	v_add_f32_e32 v185, 1.0, v185
	v_fma_f32 v204, v182, v204, v102
	v_fma_f32 v205, v183, v205, v103
	v_fma_f32 v206, v184, v206, v104
	v_fma_f32 v207, v185, v207, v105
	v_cvt_pk_bf16_f32 v210, v204, v205
	v_cvt_pk_bf16_f32 v211, v206, v207
	s_add_u32 s14, s72, 0x2000
	s_addc_u32 s15, s73, 0
	global_store_dwordx2 v195, v[210:211], s[14:15]
	v_mul_f32_e32 v204, v42, v203
	v_mul_f32_e32 v205, v43, v203
	v_mul_f32_e32 v206, v44, v203
	v_mul_f32_e32 v207, v45, v203
	v_mul_f32_e32 v204, v58, v204
	v_mul_f32_e32 v205, v59, v205
	v_mul_f32_e32 v206, v60, v206
	v_mul_f32_e32 v207, v61, v207
	v_add_f32_e32 v186, 1.0, v186
	v_add_f32_e32 v187, 1.0, v187
	v_add_f32_e32 v188, 1.0, v188
	v_add_f32_e32 v189, 1.0, v189
	v_fma_f32 v204, v186, v204, v106
	v_fma_f32 v205, v187, v205, v107
	v_fma_f32 v206, v188, v206, v108
	v_fma_f32 v207, v189, v207, v109
	v_cvt_pk_bf16_f32 v208, v204, v205
	v_cvt_pk_bf16_f32 v209, v206, v207
	s_add_u32 s14, s72, 0x4000
	s_addc_u32 s15, s73, 0
	global_store_dwordx2 v195, v[208:209], s[14:15]
	v_mul_f32_e32 v204, v46, v203
	v_mul_f32_e32 v205, v47, v203
	v_mul_f32_e32 v206, v48, v203
	v_mul_f32_e32 v207, v49, v203
	v_mul_f32_e32 v204, v62, v204
	v_mul_f32_e32 v205, v63, v205
	v_mul_f32_e32 v206, v64, v206
	v_mul_f32_e32 v207, v65, v207
	v_add_f32_e32 v190, 1.0, v190
	v_add_f32_e32 v191, 1.0, v191
	v_add_f32_e32 v192, 1.0, v192
	v_add_f32_e32 v193, 1.0, v193
	v_fma_f32 v204, v190, v204, v110
	v_fma_f32 v205, v191, v205, v111
	v_fma_f32 v206, v192, v206, v112
	v_fma_f32 v207, v193, v207, v113
	v_cvt_pk_bf16_f32 v210, v204, v205
	v_cvt_pk_bf16_f32 v211, v206, v207
	s_add_u32 s14, s72, 0x6000
	s_addc_u32 s15, s73, 0
	global_store_dwordx2 v195, v[210:211], s[14:15]
	s_branch .LBB0_96

.LBB0_277:
.Lgb_gwin:
	s_waitcnt vmcnt(6)
	s_barrier
	s_mul_i32 s7, s6, 0xc000
	v_add_u32_e32 v220, s7, v80
	v_add_u32_e32 v221, s7, v79
	ds_read_b128 v[82:85], v220 offset:0
	ds_read_b128 v[86:89], v220 offset:2048
	ds_read_b128 v[90:93], v220 offset:4096
	ds_read_b128 v[94:97], v220 offset:6144
	ds_read_b128 v[98:101], v221 offset:0
	ds_read_b128 v[102:105], v221 offset:2048
	ds_read_b128 v[106:109], v221 offset:4096
	ds_read_b128 v[110:113], v221 offset:6144
	s_mul_i32 s7, s3, 0xc000
	v_add_u32_e32 v218, s7, v78
	s_nop 0
	v_readfirstlane_b32 s7, v218
	s_add_u32 m0, s7, 0x0
	v_lshl_add_u64 v[218:219], v[76:77], 0, s[4:5]
	global_load_lds_dwordx4 v[218:219], off
	s_add_u32 m0, s7, 0x2000
	v_lshl_add_u64 v[218:219], v[74:75], 0, s[4:5]
	global_load_lds_dwordx4 v[218:219], off
	s_add_u32 m0, s7, 0x4000
	v_lshl_add_u64 v[218:219], v[72:73], 0, s[4:5]
	global_load_lds_dwordx4 v[218:219], off
	s_add_u32 m0, s7, 0x6000
	v_lshl_add_u64 v[218:219], v[70:71], 0, s[4:5]
	global_load_lds_dwordx4 v[218:219], off
	s_add_u32 m0, s7, 0x8000
	v_lshl_add_u64 v[218:219], v[68:69], 0, s[4:5]
	global_load_lds_dwordx4 v[218:219], off
	s_add_u32 m0, s7, 0xa000
	v_lshl_add_u64 v[218:219], v[66:67], 0, s[4:5]
	global_load_lds_dwordx4 v[218:219], off
	ds_read_b128 v[114:117], v220 offset:1024
	ds_read_b128 v[118:121], v220 offset:3072
	ds_read_b128 v[122:125], v220 offset:5120
	ds_read_b128 v[126:129], v220 offset:7168
	ds_read_b128 v[134:137], v221 offset:1024
	ds_read_b128 v[138:141], v221 offset:3072
	ds_read_b128 v[162:165], v221 offset:5120
	ds_read_b128 v[166:169], v221 offset:7168
	s_waitcnt lgkmcnt(8)
	v_mfma_f32_16x16x32_bf16 v[62:65], v[98:101], v[82:85], v[62:65]
	v_mfma_f32_16x16x32_bf16 v[58:61], v[102:105], v[82:85], v[58:61]
	v_mfma_f32_16x16x32_bf16 v[54:57], v[106:109], v[82:85], v[54:57]
	v_mfma_f32_16x16x32_bf16 v[50:53], v[110:113], v[82:85], v[50:53]
	v_mfma_f32_16x16x32_bf16 v[46:49], v[98:101], v[86:89], v[46:49]
	v_mfma_f32_16x16x32_bf16 v[42:45], v[102:105], v[86:89], v[42:45]
	v_mfma_f32_16x16x32_bf16 v[38:41], v[106:109], v[86:89], v[38:41]
	v_mfma_f32_16x16x32_bf16 v[34:37], v[110:113], v[86:89], v[34:37]
	v_mfma_f32_16x16x32_bf16 v[30:33], v[98:101], v[90:93], v[30:33]
	v_mfma_f32_16x16x32_bf16 v[26:29], v[102:105], v[90:93], v[26:29]
	v_mfma_f32_16x16x32_bf16 v[22:25], v[106:109], v[90:93], v[22:25]
	v_mfma_f32_16x16x32_bf16 v[18:21], v[110:113], v[90:93], v[18:21]
	v_mfma_f32_16x16x32_bf16 v[14:17], v[98:101], v[94:97], v[14:17]
	v_mfma_f32_16x16x32_bf16 v[10:13], v[102:105], v[94:97], v[10:13]
	v_mfma_f32_16x16x32_bf16 v[6:9], v[106:109], v[94:97], v[6:9]
	v_mfma_f32_16x16x32_bf16 v[2:5], v[110:113], v[94:97], v[2:5]
	s_waitcnt lgkmcnt(0)
	s_add_i32 s7, s6, 1
	s_cmp_lg_u32 s6, 2
	s_cselect_b32 s6, s7, 0
	s_add_i32 s7, s3, 1
	s_cmp_lg_u32 s3, 2
	s_cselect_b32 s3, s7, 0
	s_add_u32 s4, s4, 0x80
	s_addc_u32 s5, s5, 0
.Lgbl_gwin:
	s_waitcnt vmcnt(6)
	s_barrier
	s_mul_i32 s7, s6, 0xc000
	v_add_u32_e32 v220, s7, v80
	v_add_u32_e32 v221, s7, v79
	ds_read_b128 v[82:85], v220 offset:0
	ds_read_b128 v[86:89], v220 offset:2048
	ds_read_b128 v[90:93], v220 offset:4096
	ds_read_b128 v[94:97], v220 offset:6144
	ds_read_b128 v[98:101], v221 offset:0
	ds_read_b128 v[102:105], v221 offset:2048
	ds_read_b128 v[106:109], v221 offset:4096
	ds_read_b128 v[110:113], v221 offset:6144
	s_mul_i32 s7, s3, 0xc000
	v_add_u32_e32 v218, s7, v78
	s_nop 0
	v_readfirstlane_b32 s7, v218
	v_mfma_f32_16x16x32_bf16 v[62:65], v[134:137], v[114:117], v[62:65]
	v_mfma_f32_16x16x32_bf16 v[58:61], v[138:141], v[114:117], v[58:61]
	s_add_u32 m0, s7, 0x0
	v_lshl_add_u64 v[218:219], v[76:77], 0, s[4:5]
	global_load_lds_dwordx4 v[218:219], off
	v_mfma_f32_16x16x32_bf16 v[54:57], v[162:165], v[114:117], v[54:57]
	v_mfma_f32_16x16x32_bf16 v[50:53], v[166:169], v[114:117], v[50:53]
	s_add_u32 m0, s7, 0x2000
	v_lshl_add_u64 v[218:219], v[74:75], 0, s[4:5]
	global_load_lds_dwordx4 v[218:219], off
	v_mfma_f32_16x16x32_bf16 v[46:49], v[134:137], v[118:121], v[46:49]
	v_mfma_f32_16x16x32_bf16 v[42:45], v[138:141], v[118:121], v[42:45]
	s_add_u32 m0, s7, 0x4000
	v_lshl_add_u64 v[218:219], v[72:73], 0, s[4:5]
	global_load_lds_dwordx4 v[218:219], off
	v_mfma_f32_16x16x32_bf16 v[38:41], v[162:165], v[118:121], v[38:41]
	v_mfma_f32_16x16x32_bf16 v[34:37], v[166:169], v[118:121], v[34:37]
	s_add_u32 m0, s7, 0x6000
	v_lshl_add_u64 v[218:219], v[70:71], 0, s[4:5]
	global_load_lds_dwordx4 v[218:219], off
	v_mfma_f32_16x16x32_bf16 v[30:33], v[134:137], v[122:125], v[30:33]
	v_mfma_f32_16x16x32_bf16 v[26:29], v[138:141], v[122:125], v[26:29]
	s_add_u32 m0, s7, 0x8000
	v_lshl_add_u64 v[218:219], v[68:69], 0, s[4:5]
	global_load_lds_dwordx4 v[218:219], off
	v_mfma_f32_16x16x32_bf16 v[22:25], v[162:165], v[122:125], v[22:25]
	v_mfma_f32_16x16x32_bf16 v[18:21], v[166:169], v[122:125], v[18:21]
	s_add_u32 m0, s7, 0xa000
	v_lshl_add_u64 v[218:219], v[66:67], 0, s[4:5]
	global_load_lds_dwordx4 v[218:219], off
	v_mfma_f32_16x16x32_bf16 v[14:17], v[134:137], v[126:129], v[14:17]
	v_mfma_f32_16x16x32_bf16 v[10:13], v[138:141], v[126:129], v[10:13]
	v_mfma_f32_16x16x32_bf16 v[6:9], v[162:165], v[126:129], v[6:9]
	v_mfma_f32_16x16x32_bf16 v[2:5], v[166:169], v[126:129], v[2:5]
	ds_read_b128 v[114:117], v220 offset:1024
	ds_read_b128 v[118:121], v220 offset:3072
	ds_read_b128 v[122:125], v220 offset:5120
	ds_read_b128 v[126:129], v220 offset:7168
	ds_read_b128 v[134:137], v221 offset:1024
	ds_read_b128 v[138:141], v221 offset:3072
	ds_read_b128 v[162:165], v221 offset:5120
	ds_read_b128 v[166:169], v221 offset:7168
	s_waitcnt lgkmcnt(8)
	v_mfma_f32_16x16x32_bf16 v[62:65], v[98:101], v[82:85], v[62:65]
	v_mfma_f32_16x16x32_bf16 v[58:61], v[102:105], v[82:85], v[58:61]
	v_mfma_f32_16x16x32_bf16 v[54:57], v[106:109], v[82:85], v[54:57]
	v_mfma_f32_16x16x32_bf16 v[50:53], v[110:113], v[82:85], v[50:53]
	v_mfma_f32_16x16x32_bf16 v[46:49], v[98:101], v[86:89], v[46:49]
	v_mfma_f32_16x16x32_bf16 v[42:45], v[102:105], v[86:89], v[42:45]
	v_mfma_f32_16x16x32_bf16 v[38:41], v[106:109], v[86:89], v[38:41]
	v_mfma_f32_16x16x32_bf16 v[34:37], v[110:113], v[86:89], v[34:37]
	v_mfma_f32_16x16x32_bf16 v[30:33], v[98:101], v[90:93], v[30:33]
	v_mfma_f32_16x16x32_bf16 v[26:29], v[102:105], v[90:93], v[26:29]
	v_mfma_f32_16x16x32_bf16 v[22:25], v[106:109], v[90:93], v[22:25]
	v_mfma_f32_16x16x32_bf16 v[18:21], v[110:113], v[90:93], v[18:21]
	v_mfma_f32_16x16x32_bf16 v[14:17], v[98:101], v[94:97], v[14:17]
	v_mfma_f32_16x16x32_bf16 v[10:13], v[102:105], v[94:97], v[10:13]
	v_mfma_f32_16x16x32_bf16 v[6:9], v[106:109], v[94:97], v[6:9]
	v_mfma_f32_16x16x32_bf16 v[2:5], v[110:113], v[94:97], v[2:5]
	s_waitcnt lgkmcnt(0)
	s_add_i32 s7, s6, 1
	s_cmp_lg_u32 s6, 2
	s_cselect_b32 s6, s7, 0
	s_add_i32 s7, s3, 1
	s_cmp_lg_u32 s3, 2
	s_cselect_b32 s3, s7, 0
	s_add_u32 s4, s4, 0x80
	s_addc_u32 s5, s5, 0
	s_cmpk_lg_i32 s4, 0x700
	s_cbranch_scc1 .Lgbl_gwin
	s_waitcnt vmcnt(6)
	s_barrier
	s_mul_i32 s7, s6, 0xc000
	v_add_u32_e32 v220, s7, v80
	v_add_u32_e32 v221, s7, v79
	ds_read_b128 v[82:85], v220 offset:0
	ds_read_b128 v[86:89], v220 offset:2048
	ds_read_b128 v[90:93], v220 offset:4096
	ds_read_b128 v[94:97], v220 offset:6144
	ds_read_b128 v[98:101], v221 offset:0
	ds_read_b128 v[102:105], v221 offset:2048
	ds_read_b128 v[106:109], v221 offset:4096
	ds_read_b128 v[110:113], v221 offset:6144
	v_mfma_f32_16x16x32_bf16 v[62:65], v[134:137], v[114:117], v[62:65]
	v_mfma_f32_16x16x32_bf16 v[58:61], v[138:141], v[114:117], v[58:61]
	v_mfma_f32_16x16x32_bf16 v[54:57], v[162:165], v[114:117], v[54:57]
	v_mfma_f32_16x16x32_bf16 v[50:53], v[166:169], v[114:117], v[50:53]
	v_mfma_f32_16x16x32_bf16 v[46:49], v[134:137], v[118:121], v[46:49]
	v_mfma_f32_16x16x32_bf16 v[42:45], v[138:141], v[118:121], v[42:45]
	v_mfma_f32_16x16x32_bf16 v[38:41], v[162:165], v[118:121], v[38:41]
	v_mfma_f32_16x16x32_bf16 v[34:37], v[166:169], v[118:121], v[34:37]
	v_mfma_f32_16x16x32_bf16 v[30:33], v[134:137], v[122:125], v[30:33]
	v_mfma_f32_16x16x32_bf16 v[26:29], v[138:141], v[122:125], v[26:29]
	v_mfma_f32_16x16x32_bf16 v[22:25], v[162:165], v[122:125], v[22:25]
	v_mfma_f32_16x16x32_bf16 v[18:21], v[166:169], v[122:125], v[18:21]
	v_mfma_f32_16x16x32_bf16 v[14:17], v[134:137], v[126:129], v[14:17]
	v_mfma_f32_16x16x32_bf16 v[10:13], v[138:141], v[126:129], v[10:13]
	v_mfma_f32_16x16x32_bf16 v[6:9], v[162:165], v[126:129], v[6:9]
	v_mfma_f32_16x16x32_bf16 v[2:5], v[166:169], v[126:129], v[2:5]
	ds_read_b128 v[114:117], v220 offset:1024
	ds_read_b128 v[118:121], v220 offset:3072
	ds_read_b128 v[122:125], v220 offset:5120
	ds_read_b128 v[126:129], v220 offset:7168
	ds_read_b128 v[134:137], v221 offset:1024
	ds_read_b128 v[138:141], v221 offset:3072
	ds_read_b128 v[162:165], v221 offset:5120
	ds_read_b128 v[166:169], v221 offset:7168
	s_waitcnt lgkmcnt(8)
	v_mfma_f32_16x16x32_bf16 v[62:65], v[98:101], v[82:85], v[62:65]
	v_mfma_f32_16x16x32_bf16 v[58:61], v[102:105], v[82:85], v[58:61]
	v_mfma_f32_16x16x32_bf16 v[54:57], v[106:109], v[82:85], v[54:57]
	v_mfma_f32_16x16x32_bf16 v[50:53], v[110:113], v[82:85], v[50:53]
	v_mfma_f32_16x16x32_bf16 v[46:49], v[98:101], v[86:89], v[46:49]
	v_mfma_f32_16x16x32_bf16 v[42:45], v[102:105], v[86:89], v[42:45]
	v_mfma_f32_16x16x32_bf16 v[38:41], v[106:109], v[86:89], v[38:41]
	v_mfma_f32_16x16x32_bf16 v[34:37], v[110:113], v[86:89], v[34:37]
	v_mfma_f32_16x16x32_bf16 v[30:33], v[98:101], v[90:93], v[30:33]
	v_mfma_f32_16x16x32_bf16 v[26:29], v[102:105], v[90:93], v[26:29]
	v_mfma_f32_16x16x32_bf16 v[22:25], v[106:109], v[90:93], v[22:25]
	v_mfma_f32_16x16x32_bf16 v[18:21], v[110:113], v[90:93], v[18:21]
	v_mfma_f32_16x16x32_bf16 v[14:17], v[98:101], v[94:97], v[14:17]
	v_mfma_f32_16x16x32_bf16 v[10:13], v[102:105], v[94:97], v[10:13]
	v_mfma_f32_16x16x32_bf16 v[6:9], v[106:109], v[94:97], v[6:9]
	v_mfma_f32_16x16x32_bf16 v[2:5], v[110:113], v[94:97], v[2:5]
	s_waitcnt lgkmcnt(0)
	s_add_i32 s7, s6, 1
	s_cmp_lg_u32 s6, 2
	s_cselect_b32 s6, s7, 0
	s_add_i32 s7, s3, 1
	s_cmp_lg_u32 s3, 2
	s_cselect_b32 s3, s7, 0
	s_waitcnt vmcnt(0)
	s_barrier
	s_mul_i32 s7, s6, 0xc000
	v_add_u32_e32 v220, s7, v80
	v_add_u32_e32 v221, s7, v79
	ds_read_b128 v[82:85], v220 offset:0
	ds_read_b128 v[86:89], v220 offset:2048
	ds_read_b128 v[90:93], v220 offset:4096
	ds_read_b128 v[94:97], v220 offset:6144
	ds_read_b128 v[98:101], v221 offset:0
	ds_read_b128 v[102:105], v221 offset:2048
	ds_read_b128 v[106:109], v221 offset:4096
	ds_read_b128 v[110:113], v221 offset:6144
	v_mfma_f32_16x16x32_bf16 v[62:65], v[134:137], v[114:117], v[62:65]
	v_mfma_f32_16x16x32_bf16 v[58:61], v[138:141], v[114:117], v[58:61]
	v_mfma_f32_16x16x32_bf16 v[54:57], v[162:165], v[114:117], v[54:57]
	v_mfma_f32_16x16x32_bf16 v[50:53], v[166:169], v[114:117], v[50:53]
	v_mfma_f32_16x16x32_bf16 v[46:49], v[134:137], v[118:121], v[46:49]
	v_mfma_f32_16x16x32_bf16 v[42:45], v[138:141], v[118:121], v[42:45]
	v_mfma_f32_16x16x32_bf16 v[38:41], v[162:165], v[118:121], v[38:41]
	v_mfma_f32_16x16x32_bf16 v[34:37], v[166:169], v[118:121], v[34:37]
	v_mfma_f32_16x16x32_bf16 v[30:33], v[134:137], v[122:125], v[30:33]
	v_mfma_f32_16x16x32_bf16 v[26:29], v[138:141], v[122:125], v[26:29]
	v_mfma_f32_16x16x32_bf16 v[22:25], v[162:165], v[122:125], v[22:25]
	v_mfma_f32_16x16x32_bf16 v[18:21], v[166:169], v[122:125], v[18:21]
	v_mfma_f32_16x16x32_bf16 v[14:17], v[134:137], v[126:129], v[14:17]
	v_mfma_f32_16x16x32_bf16 v[10:13], v[138:141], v[126:129], v[10:13]
	v_mfma_f32_16x16x32_bf16 v[6:9], v[162:165], v[126:129], v[6:9]
	v_mfma_f32_16x16x32_bf16 v[2:5], v[166:169], v[126:129], v[2:5]
	ds_read_b128 v[114:117], v220 offset:1024
	ds_read_b128 v[118:121], v220 offset:3072
	ds_read_b128 v[122:125], v220 offset:5120
	ds_read_b128 v[126:129], v220 offset:7168
	ds_read_b128 v[134:137], v221 offset:1024
	ds_read_b128 v[138:141], v221 offset:3072
	ds_read_b128 v[162:165], v221 offset:5120
	ds_read_b128 v[166:169], v221 offset:7168
	s_waitcnt lgkmcnt(8)
	v_mfma_f32_16x16x32_bf16 v[62:65], v[98:101], v[82:85], v[62:65]
	v_mfma_f32_16x16x32_bf16 v[58:61], v[102:105], v[82:85], v[58:61]
	v_mfma_f32_16x16x32_bf16 v[54:57], v[106:109], v[82:85], v[54:57]
	v_mfma_f32_16x16x32_bf16 v[50:53], v[110:113], v[82:85], v[50:53]
	v_mfma_f32_16x16x32_bf16 v[46:49], v[98:101], v[86:89], v[46:49]
	v_mfma_f32_16x16x32_bf16 v[42:45], v[102:105], v[86:89], v[42:45]
	v_mfma_f32_16x16x32_bf16 v[38:41], v[106:109], v[86:89], v[38:41]
	v_mfma_f32_16x16x32_bf16 v[34:37], v[110:113], v[86:89], v[34:37]
	v_mfma_f32_16x16x32_bf16 v[30:33], v[98:101], v[90:93], v[30:33]
	v_mfma_f32_16x16x32_bf16 v[26:29], v[102:105], v[90:93], v[26:29]
	v_mfma_f32_16x16x32_bf16 v[22:25], v[106:109], v[90:93], v[22:25]
	v_mfma_f32_16x16x32_bf16 v[18:21], v[110:113], v[90:93], v[18:21]
	v_mfma_f32_16x16x32_bf16 v[14:17], v[98:101], v[94:97], v[14:17]
	v_mfma_f32_16x16x32_bf16 v[10:13], v[102:105], v[94:97], v[10:13]
	v_mfma_f32_16x16x32_bf16 v[6:9], v[106:109], v[94:97], v[6:9]
	v_mfma_f32_16x16x32_bf16 v[2:5], v[110:113], v[94:97], v[2:5]
	s_waitcnt lgkmcnt(0)
	s_add_i32 s7, s6, 1
	s_cmp_lg_u32 s6, 2
	s_cselect_b32 s6, s7, 0
	s_add_i32 s7, s3, 1
	s_cmp_lg_u32 s3, 2
	s_cselect_b32 s3, s7, 0
	v_mfma_f32_16x16x32_bf16 v[62:65], v[134:137], v[114:117], v[62:65]
	v_mfma_f32_16x16x32_bf16 v[58:61], v[138:141], v[114:117], v[58:61]
	v_mfma_f32_16x16x32_bf16 v[54:57], v[162:165], v[114:117], v[54:57]
	v_mfma_f32_16x16x32_bf16 v[50:53], v[166:169], v[114:117], v[50:53]
	v_mfma_f32_16x16x32_bf16 v[46:49], v[134:137], v[118:121], v[46:49]
	v_mfma_f32_16x16x32_bf16 v[42:45], v[138:141], v[118:121], v[42:45]
	v_mfma_f32_16x16x32_bf16 v[38:41], v[162:165], v[118:121], v[38:41]
	v_mfma_f32_16x16x32_bf16 v[34:37], v[166:169], v[118:121], v[34:37]
	v_mfma_f32_16x16x32_bf16 v[30:33], v[134:137], v[122:125], v[30:33]
	v_mfma_f32_16x16x32_bf16 v[26:29], v[138:141], v[122:125], v[26:29]
	v_mfma_f32_16x16x32_bf16 v[22:25], v[162:165], v[122:125], v[22:25]
	v_mfma_f32_16x16x32_bf16 v[18:21], v[166:169], v[122:125], v[18:21]
	v_mfma_f32_16x16x32_bf16 v[14:17], v[134:137], v[126:129], v[14:17]
	v_mfma_f32_16x16x32_bf16 v[10:13], v[138:141], v[126:129], v[10:13]
	v_mfma_f32_16x16x32_bf16 v[6:9], v[162:165], v[126:129], v[6:9]
	v_mfma_f32_16x16x32_bf16 v[2:5], v[166:169], v[126:129], v[2:5]

.LBB0_405:
	s_andn2_b64 vcc, exec, s[0:1]
	s_mov_b64 s[2:3], 0
	s_cbranch_vccnz .LBB0_417
	s_cmp_gt_i32 s21, 0
	s_mov_b64 s[0:1], -1
	s_cbranch_scc0 .LBB0_429
	v_readlane_b32 s11, v217, 0
	v_readlane_b32 s12, v214, 57
	s_and_b32 s14, s11, 7
	s_lshr_b32 s15, s11, 3
	s_mul_hi_u32 s16, s12, 0x3500000
	s_mul_i32 s12, s12, 0x3500000
	s_add_u32 s40, s48, s12
	s_addc_u32 s41, s49, s16
	s_add_u32 s40, s40, 0xf5ce000
	s_addc_u32 s41, s41, 0
	v_and_b32_e32 v141, 15, v142
	v_lshrrev_b32_e32 v139, 4, v142
	v_and_b32_e32 v139, 3, v139
	v_lshlrev_b32_e32 v140, 6, v141
	v_lshl_add_u32 v140, v139, 4, v140
	v_lshrrev_b32_e32 v139, 3, v141
	v_lshlrev_b32_e32 v139, 5, v139
	v_xor_b32_e32 v135, v140, v139
	v_lshrrev_b32_e32 v139, 7, v142
	v_lshl_add_u32 v134, v139, 12, v135
	v_lshrrev_b32_e32 v139, 6, v142
	v_and_b32_e32 v139, 1, v139
	v_lshl_add_u32 v135, v139, 12, v135
	v_add_u32_e32 v135, 0x4000, v135
	v_and_b32_e32 v141, 63, v142
	v_lshrrev_b32_e32 v139, 2, v141
	v_lshrrev_b32_e32 v140, 6, v142
	v_lshlrev_b32_e32 v139, 6, v139
	v_lshl_add_u32 v139, v140, 15, v139
	v_and_b32_e32 v140, 3, v141
	v_lshlrev_b32_e32 v140, 4, v140
	v_lshrrev_b32_e32 v141, 5, v141
	v_lshlrev_b32_e32 v141, 5, v141
	v_xor_b32_e32 v140, v140, v141
	v_add_u32_e32 v136, v139, v140
	v_add_u32_e32 v137, 0x40000, v136
	v_lshrrev_b32_e32 v139, 7, v142
	v_and_b32_e32 v141, 15, v142
	v_lshl_add_u32 v139, v139, 6, v141
	v_mul_u32_u24_e32 v139, 0x1600, v139
	v_lshrrev_b32_e32 v140, 6, v142
	v_and_b32_e32 v140, 1, v140
	v_lshlrev_b32_e32 v140, 6, v140
	v_lshrrev_b32_e32 v141, 4, v142
	v_and_b32_e32 v141, 3, v141
	v_lshl_add_u32 v140, v141, 3, v140
	v_add_u32_e32 v138, v139, v140
	v_and_b32_e32 v141, 1, v141
	v_mul_u32_u24_e32 v141, 24, v141
	v_add_u32_e32 v138, v138, v141
	v_lshlrev_b32_e32 v161, 11, v142
	v_lshrrev_b32_e32 v141, 6, v142
	v_lshlrev_b32_e32 v141, 10, v141
	s_nop 0
	v_readfirstlane_b32 s6, v141
	s_mov_b32 s10, s15

.LBB0_438:
	s_andn2_b64 vcc, exec, s[2:3]
	s_cbranch_vccnz .LBB0_463
	v_readlane_b32 s4, v217, 0
	v_readlane_b32 s5, v214, 57
	v_readlane_b32 s38, v217, 1
	v_readlane_b32 s39, v217, 2
	v_lshrrev_b32_e32 v197, 6, v142
	s_sub_u32 s38, s38, 0xd0
	s_subb_u32 s39, s39, 0
	v_readfirstlane_b32 s6, v197
	s_load_dwordx4 s[40:43], s[38:39], 0x0
	s_load_dwordx2 s[38:39], s[38:39], 0x40
	v_and_b32_e32 v194, 63, v142
	v_and_b32_e32 v195, 7, v194
	v_lshlrev_b32_e32 v195, 3, v195
	v_lshrrev_b32_e32 v197, 3, v194
	v_lshl_add_u32 v195, v197, 10, v195
	v_lshlrev_b32_e32 v194, 4, v194
	v_mov_b32_e32 v196, 0x358637bd
	s_lshr_b32 s7, s4, 3
	s_lshl_b32 s7, s7, 3
	s_add_u32 s7, s7, s6
	s_and_b32 s10, s4, 7
	s_mul_i32 s10, s10, 192
	s_add_u32 s11, s7, 0
	s_mul_i32 s12, s11, 43691
	s_lshr_b32 s12, s12, 23
	s_mul_i32 s12, s12, 1344
	s_add_u32 s11, s11, s12
	s_add_u32 s98, s11, s10
	s_add_u32 s11, s7, 256
	s_mul_i32 s12, s11, 43691
	s_lshr_b32 s12, s12, 23
	s_mul_i32 s12, s12, 1344
	s_add_u32 s11, s11, s12
	s_add_u32 s99, s11, s10
	s_add_u32 s11, s7, 512
	s_mul_i32 s12, s11, 43691
	s_lshr_b32 s12, s12, 23
	s_mul_i32 s12, s12, 1344
	s_add_u32 s11, s11, s12
	s_add_u32 s17, s11, s10
	s_waitcnt lgkmcnt(0)
	s_lshl_b32 s11, s98, 12
	s_add_u32 s68, s48, s11
	s_addc_u32 s69, s49, 0
	s_cmp_lg_u32 s5, 0
	s_cbranch_scc1 .Lnrm_n0_x0
	s_add_u32 s68, s40, s11
	s_addc_u32 s69, s41, 0
	s_cmp_lt_u32 s98, 0x1000
	s_cbranch_scc1 .Lnrm_n0_x0
	s_sub_u32 s11, s11, 0x1000000
	s_add_u32 s68, s42, s11
	s_addc_u32 s69, s43, 0

.Lnrm_n0_x2:
	global_load_dwordx4 v[34:37], v194, s[72:73] offset:0
	global_load_dwordx4 v[38:41], v194, s[72:73] offset:1024
	global_load_dwordx4 v[42:45], v194, s[72:73] offset:2048
	global_load_dwordx4 v[46:49], v194, s[72:73] offset:3072
	s_mov_b32 s42, s17
	s_mul_i32 s11, s5, 3
	s_add_u32 s11, s11, 0
	s_lshl_b32 s11, s11, 12
	s_add_u32 s38, s38, s11
	s_addc_u32 s39, s39, 0
	global_load_dwordx4 v[50:53], v194, s[38:39] offset:0
	global_load_dwordx4 v[54:57], v194, s[38:39] offset:1024
	global_load_dwordx4 v[58:61], v194, s[38:39] offset:2048
	global_load_dwordx4 v[62:65], v194, s[38:39] offset:3072
	s_sub_u32 s11, s98, 0x1000
	s_lshr_b32 s11, s11, 10
	s_add_u32 s11, s11, 1
	s_cmp_lt_u32 s98, 0x1000
	s_cselect_b32 s11, 0, s11
	s_mul_i32 s12, s5, 3
	s_add_u32 s11, s11, s12
	s_mul_i32 s11, s11, 0x9000
	s_add_u32 s11, s11, 0x0
	s_add_u32 s74, s34, s11
	s_addc_u32 s75, s35, 0
	s_add_u32 s80, s74, 0x1000
	s_addc_u32 s81, s75, 0
	global_load_dwordx4 v[66:69], v194, s[74:75] offset:0
	global_load_dwordx4 v[70:73], v194, s[74:75] offset:1024
	global_load_dwordx4 v[74:77], v194, s[74:75] offset:2048
	global_load_dwordx4 v[78:81], v194, s[74:75] offset:3072
	global_load_dwordx4 v[114:117], v194, s[80:81] offset:0
	global_load_dwordx4 v[118:121], v194, s[80:81] offset:1024
	global_load_dwordx4 v[122:125], v194, s[80:81] offset:2048
	global_load_dwordx4 v[126:129], v194, s[80:81] offset:3072
	s_sub_u32 s11, s99, 0x1000
	s_lshr_b32 s11, s11, 10
	s_add_u32 s11, s11, 1
	s_cmp_lt_u32 s99, 0x1000
	s_cselect_b32 s11, 0, s11
	s_mul_i32 s12, s5, 3
	s_add_u32 s11, s11, s12
	s_mul_i32 s11, s11, 0x9000
	s_add_u32 s11, s11, 0x0
	s_add_u32 s76, s34, s11
	s_addc_u32 s77, s35, 0
	s_add_u32 s82, s76, 0x1000
	s_addc_u32 s83, s77, 0
	global_load_dwordx4 v[82:85], v194, s[76:77] offset:0
	global_load_dwordx4 v[86:89], v194, s[76:77] offset:1024
	global_load_dwordx4 v[90:93], v194, s[76:77] offset:2048
	global_load_dwordx4 v[94:97], v194, s[76:77] offset:3072
	global_load_dwordx4 v[162:165], v194, s[82:83] offset:0
	global_load_dwordx4 v[166:169], v194, s[82:83] offset:1024
	global_load_dwordx4 v[170:173], v194, s[82:83] offset:2048
	global_load_dwordx4 v[174:177], v194, s[82:83] offset:3072
	s_sub_u32 s11, s42, 0x1000
	s_lshr_b32 s11, s11, 10
	s_add_u32 s11, s11, 1
	s_cmp_lt_u32 s42, 0x1000
	s_cselect_b32 s11, 0, s11
	s_mul_i32 s12, s5, 3
	s_add_u32 s11, s11, s12
	s_mul_i32 s11, s11, 0x9000
	s_add_u32 s11, s11, 0x0
	s_add_u32 s78, s34, s11
	s_addc_u32 s79, s35, 0
	s_add_u32 s92, s78, 0x1000
	s_addc_u32 s93, s79, 0
	global_load_dwordx4 v[98:101], v194, s[78:79] offset:0
	global_load_dwordx4 v[102:105], v194, s[78:79] offset:1024
	global_load_dwordx4 v[106:109], v194, s[78:79] offset:2048
	global_load_dwordx4 v[110:113], v194, s[78:79] offset:3072
	global_load_dwordx4 v[178:181], v194, s[92:93] offset:0
	global_load_dwordx4 v[182:185], v194, s[92:93] offset:1024
	global_load_dwordx4 v[186:189], v194, s[92:93] offset:2048
	global_load_dwordx4 v[190:193], v194, s[92:93] offset:3072
	s_waitcnt vmcnt(28)
	s_lshr_b32 s11, s98, 4
	s_lshl_b32 s11, s11, 15
	s_and_b32 s12, s98, 15
	s_lshl_b32 s12, s12, 6
	s_add_u32 s11, s11, s12
	s_add_u32 s68, s24, s11
	s_addc_u32 s69, s25, 0
	s_lshr_b32 s11, s99, 4
	s_lshl_b32 s11, s11, 15
	s_and_b32 s12, s99, 15
	s_lshl_b32 s12, s12, 6
	s_add_u32 s11, s11, s12
	s_add_u32 s70, s24, s11
	s_addc_u32 s71, s25, 0
	s_lshr_b32 s11, s42, 4
	s_lshl_b32 s11, s11, 15
	s_and_b32 s12, s42, 15
	s_lshl_b32 s12, s12, 6
	s_add_u32 s11, s11, s12
	s_add_u32 s72, s24, s11
	s_addc_u32 s73, s25, 0
	v_mul_f32_e32 v198, v2, v2
	v_mul_f32_e32 v199, v18, v18
	v_mul_f32_e32 v200, v34, v34
	v_fmac_f32_e32 v198, v3, v3
	v_fmac_f32_e32 v199, v19, v19
	v_fmac_f32_e32 v200, v35, v35
	v_fmac_f32_e32 v198, v4, v4
	v_fmac_f32_e32 v199, v20, v20
	v_fmac_f32_e32 v200, v36, v36
	v_fmac_f32_e32 v198, v5, v5
	v_fmac_f32_e32 v199, v21, v21
	v_fmac_f32_e32 v200, v37, v37
	v_fmac_f32_e32 v198, v6, v6
	v_fmac_f32_e32 v199, v22, v22
	v_fmac_f32_e32 v200, v38, v38
	v_fmac_f32_e32 v198, v7, v7
	v_fmac_f32_e32 v199, v23, v23
	v_fmac_f32_e32 v200, v39, v39
	v_fmac_f32_e32 v198, v8, v8
	v_fmac_f32_e32 v199, v24, v24
	v_fmac_f32_e32 v200, v40, v40
	v_fmac_f32_e32 v198, v9, v9
	v_fmac_f32_e32 v199, v25, v25
	v_fmac_f32_e32 v200, v41, v41
	v_fmac_f32_e32 v198, v10, v10
	v_fmac_f32_e32 v199, v26, v26
	v_fmac_f32_e32 v200, v42, v42
	v_fmac_f32_e32 v198, v11, v11
	v_fmac_f32_e32 v199, v27, v27
	v_fmac_f32_e32 v200, v43, v43
	v_fmac_f32_e32 v198, v12, v12
	v_fmac_f32_e32 v199, v28, v28
	v_fmac_f32_e32 v200, v44, v44
	v_fmac_f32_e32 v198, v13, v13
	v_fmac_f32_e32 v199, v29, v29
	v_fmac_f32_e32 v200, v45, v45
	v_fmac_f32_e32 v198, v14, v14
	v_fmac_f32_e32 v199, v30, v30
	v_fmac_f32_e32 v200, v46, v46
	v_fmac_f32_e32 v198, v15, v15
	v_fmac_f32_e32 v199, v31, v31
	v_fmac_f32_e32 v200, v47, v47
	v_fmac_f32_e32 v198, v16, v16
	v_fmac_f32_e32 v199, v32, v32
	v_fmac_f32_e32 v200, v48, v48
	v_fmac_f32_e32 v198, v17, v17
	v_fmac_f32_e32 v199, v33, v33
	v_fmac_f32_e32 v200, v49, v49
	s_nop 1
	v_add_f32_dpp v198, v198, v198 quad_perm:[1,0,3,2] row_mask:0xf bank_mask:0xf
	v_add_f32_dpp v199, v199, v199 quad_perm:[1,0,3,2] row_mask:0xf bank_mask:0xf
	v_add_f32_dpp v200, v200, v200 quad_perm:[1,0,3,2] row_mask:0xf bank_mask:0xf
	s_nop 1
	v_add_f32_dpp v198, v198, v198 quad_perm:[2,3,0,1] row_mask:0xf bank_mask:0xf
	v_add_f32_dpp v199, v199, v199 quad_perm:[2,3,0,1] row_mask:0xf bank_mask:0xf
	v_add_f32_dpp v200, v200, v200 quad_perm:[2,3,0,1] row_mask:0xf bank_mask:0xf
	s_nop 1
	v_add_f32_dpp v198, v198, v198 row_half_mirror row_mask:0xf bank_mask:0xf
	v_add_f32_dpp v199, v199, v199 row_half_mirror row_mask:0xf bank_mask:0xf
	v_add_f32_dpp v200, v200, v200 row_half_mirror row_mask:0xf bank_mask:0xf
	s_nop 1
	v_add_f32_dpp v198, v198, v198 row_mirror row_mask:0xf bank_mask:0xf
	v_add_f32_dpp v199, v199, v199 row_mirror row_mask:0xf bank_mask:0xf
	v_add_f32_dpp v200, v200, v200 row_mirror row_mask:0xf bank_mask:0xf
	s_nop 1
	v_add_f32_dpp v198, v198, v198 row_bcast:15 row_mask:0xa bank_mask:0xf
	v_add_f32_dpp v199, v199, v199 row_bcast:15 row_mask:0xa bank_mask:0xf
	v_add_f32_dpp v200, v200, v200 row_bcast:15 row_mask:0xa bank_mask:0xf
	s_nop 1
	v_add_f32_dpp v198, v198, v198 row_bcast:31 row_mask:0xc bank_mask:0xf
	v_add_f32_dpp v199, v199, v199 row_bcast:31 row_mask:0xc bank_mask:0xf
	v_add_f32_dpp v200, v200, v200 row_bcast:31 row_mask:0xc bank_mask:0xf
	s_nop 1
	v_readlane_b32 s32, v198, 63
	v_readlane_b32 s20, v199, 63
	v_readlane_b32 s94, v200, 63
	s_nop 0
	v_mov_b32_e32 v201, s32
	v_mov_b32_e32 v202, s20
	v_mov_b32_e32 v203, s94
	v_fmamk_f32 v201, v201, 0x3a800000, v196
	v_fmamk_f32 v202, v202, 0x3a800000, v196
	v_fmamk_f32 v203, v203, 0x3a800000, v196
	v_rsq_f32_e32 v201, v201
	v_rsq_f32_e32 v202, v202
	v_rsq_f32_e32 v203, v203
	s_waitcnt vmcnt(0)
	v_mul_f32_e32 v204, v2, v201
	v_mul_f32_e32 v205, v3, v201
	v_mul_f32_e32 v206, v4, v201
	v_mul_f32_e32 v207, v5, v201
	v_mul_f32_e32 v204, v50, v204
	v_mul_f32_e32 v205, v51, v205
	v_mul_f32_e32 v206, v52, v206
	v_mul_f32_e32 v207, v53, v207
	v_add_f32_e32 v114, 1.0, v114
	v_add_f32_e32 v115, 1.0, v115
	v_add_f32_e32 v116, 1.0, v116
	v_add_f32_e32 v117, 1.0, v117
	v_fma_f32 v204, v114, v204, v66
	v_fma_f32 v205, v115, v205, v67
	v_fma_f32 v206, v116, v206, v68
	v_fma_f32 v207, v117, v207, v69
	v_cvt_pk_bf16_f32 v208, v204, v205
	v_cvt_pk_bf16_f32 v209, v206, v207
	s_add_u32 s14, s68, 0x0
	s_addc_u32 s15, s69, 0
	global_store_dwordx2 v195, v[208:209], s[14:15]
	v_mul_f32_e32 v204, v6, v201
	v_mul_f32_e32 v205, v7, v201
	v_mul_f32_e32 v206, v8, v201
	v_mul_f32_e32 v207, v9, v201
	v_mul_f32_e32 v204, v54, v204
	v_mul_f32_e32 v205, v55, v205
	v_mul_f32_e32 v206, v56, v206
	v_mul_f32_e32 v207, v57, v207
	v_add_f32_e32 v118, 1.0, v118
	v_add_f32_e32 v119, 1.0, v119
	v_add_f32_e32 v120, 1.0, v120
	v_add_f32_e32 v121, 1.0, v121
	v_fma_f32 v204, v118, v204, v70
	v_fma_f32 v205, v119, v205, v71
	v_fma_f32 v206, v120, v206, v72
	v_fma_f32 v207, v121, v207, v73
	v_cvt_pk_bf16_f32 v210, v204, v205
	v_cvt_pk_bf16_f32 v211, v206, v207
	s_add_u32 s14, s68, 0x2000
	s_addc_u32 s15, s69, 0
	global_store_dwordx2 v195, v[210:211], s[14:15]
	v_mul_f32_e32 v204, v10, v201
	v_mul_f32_e32 v205, v11, v201
	v_mul_f32_e32 v206, v12, v201
	v_mul_f32_e32 v207, v13, v201
	v_mul_f32_e32 v204, v58, v204
	v_mul_f32_e32 v205, v59, v205
	v_mul_f32_e32 v206, v60, v206
	v_mul_f32_e32 v207, v61, v207
	v_add_f32_e32 v122, 1.0, v122
	v_add_f32_e32 v123, 1.0, v123
	v_add_f32_e32 v124, 1.0, v124
	v_add_f32_e32 v125, 1.0, v125
	v_fma_f32 v204, v122, v204, v74
	v_fma_f32 v205, v123, v205, v75
	v_fma_f32 v206, v124, v206, v76
	v_fma_f32 v207, v125, v207, v77
	v_cvt_pk_bf16_f32 v208, v204, v205
	v_cvt_pk_bf16_f32 v209, v206, v207
	s_add_u32 s14, s68, 0x4000
	s_addc_u32 s15, s69, 0
	global_store_dwordx2 v195, v[208:209], s[14:15]
	v_mul_f32_e32 v204, v14, v201
	v_mul_f32_e32 v205, v15, v201
	v_mul_f32_e32 v206, v16, v201
	v_mul_f32_e32 v207, v17, v201
	v_mul_f32_e32 v204, v62, v204
	v_mul_f32_e32 v205, v63, v205
	v_mul_f32_e32 v206, v64, v206
	v_mul_f32_e32 v207, v65, v207
	v_add_f32_e32 v126, 1.0, v126
	v_add_f32_e32 v127, 1.0, v127
	v_add_f32_e32 v128, 1.0, v128
	v_add_f32_e32 v129, 1.0, v129
	v_fma_f32 v204, v126, v204, v78
	v_fma_f32 v205, v127, v205, v79
	v_fma_f32 v206, v128, v206, v80
	v_fma_f32 v207, v129, v207, v81
	v_cvt_pk_bf16_f32 v210, v204, v205
	v_cvt_pk_bf16_f32 v211, v206, v207
	s_add_u32 s14, s68, 0x6000
	s_addc_u32 s15, s69, 0
	global_store_dwordx2 v195, v[210:211], s[14:15]
	v_mul_f32_e32 v204, v18, v202
	v_mul_f32_e32 v205, v19, v202
	v_mul_f32_e32 v206, v20, v202
	v_mul_f32_e32 v207, v21, v202
	v_mul_f32_e32 v204, v50, v204
	v_mul_f32_e32 v205, v51, v205
	v_mul_f32_e32 v206, v52, v206
	v_mul_f32_e32 v207, v53, v207
	v_add_f32_e32 v162, 1.0, v162
	v_add_f32_e32 v163, 1.0, v163
	v_add_f32_e32 v164, 1.0, v164
	v_add_f32_e32 v165, 1.0, v165
	v_fma_f32 v204, v162, v204, v82
	v_fma_f32 v205, v163, v205, v83
	v_fma_f32 v206, v164, v206, v84
	v_fma_f32 v207, v165, v207, v85
	v_cvt_pk_bf16_f32 v208, v204, v205
	v_cvt_pk_bf16_f32 v209, v206, v207
	s_add_u32 s14, s70, 0x0
	s_addc_u32 s15, s71, 0
	global_store_dwordx2 v195, v[208:209], s[14:15]
	v_mul_f32_e32 v204, v22, v202
	v_mul_f32_e32 v205, v23, v202
	v_mul_f32_e32 v206, v24, v202
	v_mul_f32_e32 v207, v25, v202
	v_mul_f32_e32 v204, v54, v204
	v_mul_f32_e32 v205, v55, v205
	v_mul_f32_e32 v206, v56, v206
	v_mul_f32_e32 v207, v57, v207
	v_add_f32_e32 v166, 1.0, v166
	v_add_f32_e32 v167, 1.0, v167
	v_add_f32_e32 v168, 1.0, v168
	v_add_f32_e32 v169, 1.0, v169
	v_fma_f32 v204, v166, v204, v86
	v_fma_f32 v205, v167, v205, v87
	v_fma_f32 v206, v168, v206, v88
	v_fma_f32 v207, v169, v207, v89
	v_cvt_pk_bf16_f32 v210, v204, v205
	v_cvt_pk_bf16_f32 v211, v206, v207
	s_add_u32 s14, s70, 0x2000
	s_addc_u32 s15, s71, 0
	global_store_dwordx2 v195, v[210:211], s[14:15]
	v_mul_f32_e32 v204, v26, v202
	v_mul_f32_e32 v205, v27, v202
	v_mul_f32_e32 v206, v28, v202
	v_mul_f32_e32 v207, v29, v202
	v_mul_f32_e32 v204, v58, v204
	v_mul_f32_e32 v205, v59, v205
	v_mul_f32_e32 v206, v60, v206
	v_mul_f32_e32 v207, v61, v207
	v_add_f32_e32 v170, 1.0, v170
	v_add_f32_e32 v171, 1.0, v171
	v_add_f32_e32 v172, 1.0, v172
	v_add_f32_e32 v173, 1.0, v173
	v_fma_f32 v204, v170, v204, v90
	v_fma_f32 v205, v171, v205, v91
	v_fma_f32 v206, v172, v206, v92
	v_fma_f32 v207, v173, v207, v93
	v_cvt_pk_bf16_f32 v208, v204, v205
	v_cvt_pk_bf16_f32 v209, v206, v207
	s_add_u32 s14, s70, 0x4000
	s_addc_u32 s15, s71, 0
	global_store_dwordx2 v195, v[208:209], s[14:15]
	v_mul_f32_e32 v204, v30, v202
	v_mul_f32_e32 v205, v31, v202
	v_mul_f32_e32 v206, v32, v202
	v_mul_f32_e32 v207, v33, v202
	v_mul_f32_e32 v204, v62, v204
	v_mul_f32_e32 v205, v63, v205
	v_mul_f32_e32 v206, v64, v206
	v_mul_f32_e32 v207, v65, v207
	v_add_f32_e32 v174, 1.0, v174
	v_add_f32_e32 v175, 1.0, v175
	v_add_f32_e32 v176, 1.0, v176
	v_add_f32_e32 v177, 1.0, v177
	v_fma_f32 v204, v174, v204, v94
	v_fma_f32 v205, v175, v205, v95
	v_fma_f32 v206, v176, v206, v96
	v_fma_f32 v207, v177, v207, v97
	v_cvt_pk_bf16_f32 v210, v204, v205
	v_cvt_pk_bf16_f32 v211, v206, v207
	s_add_u32 s14, s70, 0x6000
	s_addc_u32 s15, s71, 0
	global_store_dwordx2 v195, v[210:211], s[14:15]
	v_mul_f32_e32 v204, v34, v203
	v_mul_f32_e32 v205, v35, v203
	v_mul_f32_e32 v206, v36, v203
	v_mul_f32_e32 v207, v37, v203
	v_mul_f32_e32 v204, v50, v204
	v_mul_f32_e32 v205, v51, v205
	v_mul_f32_e32 v206, v52, v206
	v_mul_f32_e32 v207, v53, v207
	v_add_f32_e32 v178, 1.0, v178
	v_add_f32_e32 v179, 1.0, v179
	v_add_f32_e32 v180, 1.0, v180
	v_add_f32_e32 v181, 1.0, v181
	v_fma_f32 v204, v178, v204, v98
	v_fma_f32 v205, v179, v205, v99
	v_fma_f32 v206, v180, v206, v100
	v_fma_f32 v207, v181, v207, v101
	v_cvt_pk_bf16_f32 v208, v204, v205
	v_cvt_pk_bf16_f32 v209, v206, v207
	s_add_u32 s14, s72, 0x0
	s_addc_u32 s15, s73, 0
	global_store_dwordx2 v195, v[208:209], s[14:15]
	v_mul_f32_e32 v204, v38, v203
	v_mul_f32_e32 v205, v39, v203
	v_mul_f32_e32 v206, v40, v203
	v_mul_f32_e32 v207, v41, v203
	v_mul_f32_e32 v204, v54, v204
	v_mul_f32_e32 v205, v55, v205
	v_mul_f32_e32 v206, v56, v206
	v_mul_f32_e32 v207, v57, v207
	v_add_f32_e32 v182, 1.0, v182
	v_add_f32_e32 v183, 1.0, v183
	v_add_f32_e32 v184, 1.0, v184
	v_add_f32_e32 v185, 1.0, v185
	v_fma_f32 v204, v182, v204, v102
	v_fma_f32 v205, v183, v205, v103
	v_fma_f32 v206, v184, v206, v104
	v_fma_f32 v207, v185, v207, v105
	v_cvt_pk_bf16_f32 v210, v204, v205
	v_cvt_pk_bf16_f32 v211, v206, v207
	s_add_u32 s14, s72, 0x2000
	s_addc_u32 s15, s73, 0
	global_store_dwordx2 v195, v[210:211], s[14:15]
	v_mul_f32_e32 v204, v42, v203
	v_mul_f32_e32 v205, v43, v203
	v_mul_f32_e32 v206, v44, v203
	v_mul_f32_e32 v207, v45, v203
	v_mul_f32_e32 v204, v58, v204
	v_mul_f32_e32 v205, v59, v205
	v_mul_f32_e32 v206, v60, v206
	v_mul_f32_e32 v207, v61, v207
	v_add_f32_e32 v186, 1.0, v186
	v_add_f32_e32 v187, 1.0, v187
	v_add_f32_e32 v188, 1.0, v188
	v_add_f32_e32 v189, 1.0, v189
	v_fma_f32 v204, v186, v204, v106
	v_fma_f32 v205, v187, v205, v107
	v_fma_f32 v206, v188, v206, v108
	v_fma_f32 v207, v189, v207, v109
	v_cvt_pk_bf16_f32 v208, v204, v205
	v_cvt_pk_bf16_f32 v209, v206, v207
	s_add_u32 s14, s72, 0x4000
	s_addc_u32 s15, s73, 0
	global_store_dwordx2 v195, v[208:209], s[14:15]
	v_mul_f32_e32 v204, v46, v203
	v_mul_f32_e32 v205, v47, v203
	v_mul_f32_e32 v206, v48, v203
	v_mul_f32_e32 v207, v49, v203
	v_mul_f32_e32 v204, v62, v204
	v_mul_f32_e32 v205, v63, v205
	v_mul_f32_e32 v206, v64, v206
	v_mul_f32_e32 v207, v65, v207
	v_add_f32_e32 v190, 1.0, v190
	v_add_f32_e32 v191, 1.0, v191
	v_add_f32_e32 v192, 1.0, v192
	v_add_f32_e32 v193, 1.0, v193
	v_fma_f32 v204, v190, v204, v110
	v_fma_f32 v205, v191, v205, v111
	v_fma_f32 v206, v192, v206, v112
	v_fma_f32 v207, v193, v207, v113
	v_cvt_pk_bf16_f32 v210, v204, v205
	v_cvt_pk_bf16_f32 v211, v206, v207
	s_add_u32 s14, s72, 0x6000
	s_addc_u32 s15, s73, 0
	global_store_dwordx2 v195, v[210:211], s[14:15]
	s_branch .LBB0_463

.LBB0_466:
	s_or_b64 exec, exec, s[0:1]
	v_cmp_eq_u32_e32 vcc, 0x1600, v11
	s_nop 1
	v_cndmask_b32_e64 v166, 0, 1, vcc
	v_mul_i32_i24_e32 v14, v4, v10
	v_mad_u64_u32 v[14:15], s[0:1], v14, v11, 0
	v_mul_hi_i32_i24_e32 v13, v4, v10
	v_mov_b32_e32 v38, v15
	v_mad_u64_u32 v[38:39], s[0:1], v13, v11, v[38:39]
	v_mov_b32_e32 v15, v38
	v_lshl_add_u64 v[6:7], v[14:15], 2, v[6:7]
	v_lshlrev_b32_sdwa v14, v159, sext(v9) dst_sel:DWORD dst_unused:UNUSED_PAD src0_sel:DWORD src1_sel:WORD_0
	v_bfe_u32 v13, v5, 4, 4
	v_ashrrev_i32_e32 v9, 31, v8
	v_or_b32_e32 v15, v13, v14
	v_lshl_add_u64 v[46:47], v[8:9], 2, v[6:7]
	v_or_b32_e32 v8, 16, v15
	v_mul_hi_i32_i24_e32 v7, v15, v11
	v_mul_i32_i24_e32 v6, v15, v11
	v_mul_hi_i32_i24_e32 v9, v8, v11
	v_mul_i32_i24_e32 v8, v8, v11
	v_lshl_add_u64 v[6:7], v[6:7], 2, v[46:47]
	v_lshl_add_u64 v[38:39], v[8:9], 2, v[46:47]
	s_waitcnt vmcnt(0)
	s_barrier
	global_load_dwordx4 v[6:9], v[6:7], off nt
	s_nop 0
	global_load_dwordx4 v[38:41], v[38:39], off nt
	v_or_b32_e32 v37, 32, v15
	v_mul_hi_i32_i24_e32 v43, v37, v11
	v_mul_i32_i24_e32 v42, v37, v11
	v_lshl_add_u64 v[42:43], v[42:43], 2, v[46:47]
	v_or_b32_e32 v15, 48, v15
	global_load_dwordx4 v[42:45], v[42:43], off nt
	v_mul_hi_i32_i24_e32 v49, v15, v11
	v_mul_i32_i24_e32 v48, v15, v11
	v_lshl_add_u64 v[46:47], v[48:49], 2, v[46:47]
	global_load_dwordx4 v[46:49], v[46:47], off nt
	v_readlane_b32 s0, v217, 7
	v_readlane_b32 s1, v217, 8
	v_lshrrev_b32_e32 v15, 8, v5
	v_bfe_u32 v37, v5, 2, 6
	v_mov_b64_e32 v[50:51], s[0:1]
	s_mov_b32 s0, 0x3500000
	v_mad_i64_i32 v[10:11], s[0:1], v10, s0, v[50:51]
	v_lshlrev_b32_e32 v52, 4, v5
	s_movk_i32 s0, 0x4100
	v_lshlrev_b32_e32 v12, 2, v12
	v_and_b32_e32 v53, 0xfc, v5
	v_mad_i32_i24 v50, v15, s0, 0
	v_mul_u32_u24_e32 v5, 0x104, v13
	v_and_b32_e32 v13, 48, v52
	v_or_b32_e32 v0, v37, v0
	v_mov_b32_e32 v169, v0
	v_lshl_add_u64 v[2:3], v[2:3], 1, v[10:11]
	v_mov_b32_e32 v167, v2
	v_mov_b32_e32 v168, v3
	v_add3_u32 v12, v50, v12, v5
	v_mul_u32_u24_e32 v10, 0x104, v13
	v_mul_hi_i32_i24_e32 v5, v4, v0
	v_mul_i32_i24_e32 v4, v4, v0
	v_ashrrev_i32_e32 v15, 31, v14
	v_lshlrev_b32_e32 v0, 1, v13
	v_add_u32_e32 v13, 0x1040, v12
	v_add3_u32 v50, v50, v10, v53
	v_lshl_add_u64 v[2:3], v[4:5], 1, v[2:3]
	v_add_u32_e32 v37, 0x1048, v12
	v_add_u32_e32 v51, 0x2080, v12
	v_add_u32_e32 v52, 0x2088, v12
	v_add_u32_e32 v54, 0x30c0, v12
	v_add_u32_e32 v55, 0x30c8, v12
	v_add_u32_e32 v53, 0x400, v50
	v_add_u32_e32 v56, 0x800, v50
	v_add_u32_e32 v57, 0xc00, v50
	v_lshl_add_u64 v[10:11], v[14:15], 1, v[2:3]
	v_lshl_add_u64 v[10:11], v[10:11], 0, v[0:1]
	v_lshlrev_b32_e32 v170, 1, v14
	v_add_u32_e32 v170, v170, v0
	v_lshrrev_b32_e32 v171, 4, v169
	v_lshlrev_b32_e32 v171, 15, v171
	v_and_b32_e32 v172, 15, v169
	v_lshl_add_u32 v171, v172, 6, v171
	v_lshrrev_b32_e32 v172, 6, v170
	v_lshl_add_u32 v171, v172, 10, v171
	v_and_b32_e32 v172, 63, v170
	v_add_u32_e32 v171, v171, v172
	v_add_co_u32_e32 v167, vcc, v167, v171
	s_nop 1
	v_addc_co_u32_e32 v168, vcc, 0, v168, vcc
	v_cmp_eq_u32_e32 vcc, 1, v166
	s_nop 1
	v_cndmask_b32_e32 v10, v10, v167, vcc
	v_cndmask_b32_e32 v11, v11, v168, vcc
	s_waitcnt vmcnt(3)
	ds_write2_b32 v12, v6, v7 offset1:1
	ds_write2_b32 v12, v8, v9 offset0:2 offset1:3
	s_waitcnt vmcnt(2)
	ds_write2_b32 v13, v38, v39 offset1:1
	ds_write2_b32 v37, v40, v41 offset1:1
	s_waitcnt vmcnt(1)
	ds_write2_b32 v51, v42, v43 offset1:1
	ds_write2_b32 v52, v44, v45 offset1:1
	s_waitcnt vmcnt(0)
	ds_write2_b32 v54, v46, v47 offset1:1
	ds_write2_b32 v55, v48, v49 offset1:1
	s_waitcnt lgkmcnt(0)
	s_barrier
	ds_read2_b32 v[2:3], v50 offset1:65
	ds_read2_b32 v[4:5], v50 offset0:130 offset1:195
	ds_read2_b32 v[6:7], v53 offset0:4 offset1:69
	ds_read2_b32 v[8:9], v53 offset0:134 offset1:199
	ds_read2_b32 v[12:13], v56 offset0:8 offset1:73
	ds_read2_b32 v[14:15], v56 offset0:138 offset1:203
	ds_read2_b32 v[38:39], v57 offset0:12 offset1:77
	ds_read2_b32 v[40:41], v57 offset0:142 offset1:207
	s_waitcnt lgkmcnt(7)
	v_cvt_pk_bf16_f32 v2, v2, v3
	s_waitcnt lgkmcnt(6)
	v_cvt_pk_bf16_f32 v3, v4, v5
	s_waitcnt lgkmcnt(5)
	v_cvt_pk_bf16_f32 v4, v6, v7
	s_waitcnt lgkmcnt(4)
	v_cvt_pk_bf16_f32 v5, v8, v9
	s_waitcnt lgkmcnt(3)
	v_cvt_pk_bf16_f32 v6, v12, v13
	s_waitcnt lgkmcnt(2)
	v_cvt_pk_bf16_f32 v7, v14, v15
	s_waitcnt lgkmcnt(1)
	v_cvt_pk_bf16_f32 v8, v38, v39
	s_waitcnt lgkmcnt(0)
	v_cvt_pk_bf16_f32 v9, v40, v41
	global_store_dwordx4 v[10:11], v[2:5], off
	global_store_dwordx4 v[10:11], v[6:9], off offset:16
